# kscale ladder in convert_tile de-serialised (32 loads hoisted, one wait) + scan MFMA fragment reads pipelined 3 pairs ahead
# speedup vs baseline: 1.0368x; 1.0091x over previous
; DI void convert_tile(const CvtJob& jb, int ti, char* lds) {
;     ...
; #pragma unroll
;   for (int i = 0; i < 32; ++i) v[i] = (n < N) ? jb.src[(size_t)(k0 + kr + 2 * i) * N + n] : 0.f;
; #pragma unroll
;   for (int i = 0; i < 32; ++i) { const int k = kr + 2 * i; tile[k * 257 + nn] = jb.kscale ? v[i] * jb.kscale[k0 + k] : v[i]; }
.LBB0_131:
	s_or_b64 exec, exec, s[40:41]
	v_readlane_b32 s4, v252, 33
	v_readlane_b32 s5, v252, 34
	s_andn2_b64 vcc, exec, s[4:5]
	s_nop 0
	v_cndmask_b32_e64 v5, 0, 1, s[4:5]
	v_cmp_ne_u32_e64 s[40:41], 1, v5
	s_cbranch_vccnz .LBB0_133
	v_ashrrev_i32_e32 v5, 31, v4
	v_lshl_add_u64 v[4:5], v[4:5], 2, s[50:51]
	s_waitcnt vmcnt(24)
	global_load_dword v100, v[4:5], off
	global_load_dword v101, v[4:5], off offset:8
	global_load_dword v102, v[4:5], off offset:16
	global_load_dword v103, v[4:5], off offset:24
	global_load_dword v104, v[4:5], off offset:32
	global_load_dword v105, v[4:5], off offset:40
	global_load_dword v106, v[4:5], off offset:48
	global_load_dword v107, v[4:5], off offset:56
	global_load_dword v108, v[4:5], off offset:64
	global_load_dword v109, v[4:5], off offset:72
	global_load_dword v110, v[4:5], off offset:80
	global_load_dword v111, v[4:5], off offset:88
	global_load_dword v112, v[4:5], off offset:96
	global_load_dword v113, v[4:5], off offset:104
	global_load_dword v114, v[4:5], off offset:112
	global_load_dword v115, v[4:5], off offset:120
	global_load_dword v116, v[4:5], off offset:128
	global_load_dword v117, v[4:5], off offset:136
	global_load_dword v118, v[4:5], off offset:144
	global_load_dword v119, v[4:5], off offset:152
	global_load_dword v120, v[4:5], off offset:160
	global_load_dword v121, v[4:5], off offset:168
	global_load_dword v122, v[4:5], off offset:176
	global_load_dword v123, v[4:5], off offset:184
	global_load_dword v124, v[4:5], off offset:192
	global_load_dword v125, v[4:5], off offset:200
	global_load_dword v126, v[4:5], off offset:208
	global_load_dword v127, v[4:5], off offset:216
	global_load_dword v128, v[4:5], off offset:224
	global_load_dword v129, v[4:5], off offset:232
	global_load_dword v130, v[4:5], off offset:240
	global_load_dword v131, v[4:5], off offset:248
	s_waitcnt vmcnt(0)
	v_mul_f32_e32 v39, v39, v100
.LBB0_133:
	v_lshl_add_u32 v4, v3, 2, 0
	s_movk_i32 s4, 0x404
	v_mad_i32_i24 v3, v2, s4, v4
	s_sub_i32 s66, s68, s66
	s_waitcnt vmcnt(0)
	ds_write_b32 v3, v39
	s_and_b64 vcc, exec, s[40:41]
	v_ashrrev_i32_e32 v3, 31, v2
	s_cbranch_vccnz .LBB0_135
	s_ashr_i32 s67, s66, 31
	v_lshl_add_u64 v[6:7], v[2:3], 0, s[66:67]
	v_lshl_add_u64 v[6:7], v[6:7], 2, s[50:51]
	v_mul_f32_e32 v36, v36, v101
.LBB0_135:
	v_mul_i32_i24_e32 v5, 0x404, v2
	v_add_u32_e32 v4, v5, v4
	s_and_b64 vcc, exec, s[40:41]
	ds_write_b32 v4, v36 offset:2056
	s_cbranch_vccnz .LBB0_137
	s_ashr_i32 s67, s66, 31
	v_lshl_add_u64 v[6:7], v[2:3], 0, s[66:67]
	v_lshl_add_u64 v[6:7], v[6:7], 2, s[50:51]
	v_mul_f32_e32 v38, v38, v102
.LBB0_137:
	s_and_b64 vcc, exec, s[40:41]
	ds_write_b32 v4, v38 offset:4112
	s_cbranch_vccnz .LBB0_139
	s_ashr_i32 s67, s66, 31
	v_lshl_add_u64 v[6:7], v[2:3], 0, s[66:67]
	v_lshl_add_u64 v[6:7], v[6:7], 2, s[50:51]
	v_mul_f32_e32 v34, v34, v103
.LBB0_139:
	s_and_b64 vcc, exec, s[40:41]
	ds_write_b32 v4, v34 offset:6168
	s_cbranch_vccnz .LBB0_141
	s_ashr_i32 s67, s66, 31
	v_lshl_add_u64 v[6:7], v[2:3], 0, s[66:67]
	v_lshl_add_u64 v[6:7], v[6:7], 2, s[50:51]
	v_mul_f32_e32 v37, v37, v104
.LBB0_141:
	s_and_b64 vcc, exec, s[40:41]
	ds_write_b32 v4, v37 offset:8224
	s_cbranch_vccnz .LBB0_143
	s_ashr_i32 s67, s66, 31
	v_lshl_add_u64 v[6:7], v[2:3], 0, s[66:67]
	v_lshl_add_u64 v[6:7], v[6:7], 2, s[50:51]
	v_mul_f32_e32 v32, v32, v105
.LBB0_143:
	s_and_b64 vcc, exec, s[40:41]
	ds_write_b32 v4, v32 offset:10280
	s_cbranch_vccnz .LBB0_145
	s_ashr_i32 s67, s66, 31
	v_lshl_add_u64 v[6:7], v[2:3], 0, s[66:67]
	v_lshl_add_u64 v[6:7], v[6:7], 2, s[50:51]
	v_mul_f32_e32 v35, v35, v106
.LBB0_145:
	s_and_b64 vcc, exec, s[40:41]
	ds_write_b32 v4, v35 offset:12336
	s_cbranch_vccnz .LBB0_147
	s_ashr_i32 s67, s66, 31
	v_lshl_add_u64 v[6:7], v[2:3], 0, s[66:67]
	v_lshl_add_u64 v[6:7], v[6:7], 2, s[50:51]
	v_mul_f32_e32 v30, v30, v107
.LBB0_147:
	s_and_b64 vcc, exec, s[40:41]
	ds_write_b32 v4, v30 offset:14392
	s_cbranch_vccnz .LBB0_149
	s_ashr_i32 s67, s66, 31
	v_lshl_add_u64 v[6:7], v[2:3], 0, s[66:67]
	v_lshl_add_u64 v[6:7], v[6:7], 2, s[50:51]
	v_mul_f32_e32 v33, v33, v108
.LBB0_149:
	s_and_b64 vcc, exec, s[40:41]
	ds_write_b32 v4, v33 offset:16448
	s_cbranch_vccnz .LBB0_151
	s_ashr_i32 s67, s66, 31
	v_lshl_add_u64 v[6:7], v[2:3], 0, s[66:67]
	v_lshl_add_u64 v[6:7], v[6:7], 2, s[50:51]
	v_mul_f32_e32 v28, v28, v109
.LBB0_151:
	s_and_b64 vcc, exec, s[40:41]
	ds_write_b32 v4, v28 offset:18504
	s_cbranch_vccnz .LBB0_153
	s_ashr_i32 s67, s66, 31
	v_lshl_add_u64 v[6:7], v[2:3], 0, s[66:67]
	v_lshl_add_u64 v[6:7], v[6:7], 2, s[50:51]
	v_mul_f32_e32 v31, v31, v110
.LBB0_153:
	s_and_b64 vcc, exec, s[40:41]
	ds_write_b32 v4, v31 offset:20560
	s_cbranch_vccnz .LBB0_155
	s_ashr_i32 s67, s66, 31
	v_lshl_add_u64 v[6:7], v[2:3], 0, s[66:67]
	v_lshl_add_u64 v[6:7], v[6:7], 2, s[50:51]
	v_mul_f32_e32 v26, v26, v111
; DI void convert_tile(const CvtJob& jb, int ti, char* lds) {
;     ...
; #pragma unroll
;   for (int i = 0; i < 32; ++i) v[i] = (n < N) ? jb.src[(size_t)(k0 + kr + 2 * i) * N + n] : 0.f;
; #pragma unroll
;   for (int i = 0; i < 32; ++i) { const int k = kr + 2 * i; tile[k * 257 + nn] = jb.kscale ? v[i] * jb.kscale[k0 + k] : v[i]; }
.LBB0_155:
	s_and_b64 vcc, exec, s[40:41]
	ds_write_b32 v4, v26 offset:22616
	s_cbranch_vccnz .LBB0_157
	s_ashr_i32 s67, s66, 31
	v_lshl_add_u64 v[6:7], v[2:3], 0, s[66:67]
	v_lshl_add_u64 v[6:7], v[6:7], 2, s[50:51]
	v_mul_f32_e32 v29, v29, v112
.LBB0_157:
	s_and_b64 vcc, exec, s[40:41]
	ds_write_b32 v4, v29 offset:24672
	s_cbranch_vccnz .LBB0_159
	s_ashr_i32 s67, s66, 31
	v_lshl_add_u64 v[6:7], v[2:3], 0, s[66:67]
	v_lshl_add_u64 v[6:7], v[6:7], 2, s[50:51]
	v_mul_f32_e32 v24, v24, v113
.LBB0_159:
	s_and_b64 vcc, exec, s[40:41]
	ds_write_b32 v4, v24 offset:26728
	s_cbranch_vccnz .LBB0_161
	s_ashr_i32 s67, s66, 31
	v_lshl_add_u64 v[6:7], v[2:3], 0, s[66:67]
	v_lshl_add_u64 v[6:7], v[6:7], 2, s[50:51]
	v_mul_f32_e32 v27, v27, v114
.LBB0_161:
	s_and_b64 vcc, exec, s[40:41]
	ds_write_b32 v4, v27 offset:28784
	s_cbranch_vccnz .LBB0_163
	s_ashr_i32 s67, s66, 31
	v_lshl_add_u64 v[6:7], v[2:3], 0, s[66:67]
	v_lshl_add_u64 v[6:7], v[6:7], 2, s[50:51]
	v_mul_f32_e32 v22, v22, v115
.LBB0_163:
	s_and_b64 vcc, exec, s[40:41]
	ds_write_b32 v4, v22 offset:30840
	s_cbranch_vccnz .LBB0_165
	s_ashr_i32 s67, s66, 31
	v_lshl_add_u64 v[6:7], v[2:3], 0, s[66:67]
	v_lshl_add_u64 v[6:7], v[6:7], 2, s[50:51]
	v_mul_f32_e32 v25, v25, v116
.LBB0_165:
	s_and_b64 vcc, exec, s[40:41]
	ds_write_b32 v4, v25 offset:32896
	s_cbranch_vccnz .LBB0_167
	s_ashr_i32 s67, s66, 31
	v_lshl_add_u64 v[6:7], v[2:3], 0, s[66:67]
	v_lshl_add_u64 v[6:7], v[6:7], 2, s[50:51]
	v_mul_f32_e32 v20, v20, v117
.LBB0_167:
	s_and_b64 vcc, exec, s[40:41]
	ds_write_b32 v4, v20 offset:34952
	s_cbranch_vccnz .LBB0_169
	s_ashr_i32 s67, s66, 31
	v_lshl_add_u64 v[6:7], v[2:3], 0, s[66:67]
	v_lshl_add_u64 v[6:7], v[6:7], 2, s[50:51]
	v_mul_f32_e32 v23, v23, v118
.LBB0_169:
	s_and_b64 vcc, exec, s[40:41]
	ds_write_b32 v4, v23 offset:37008
	s_cbranch_vccnz .LBB0_171
	s_ashr_i32 s67, s66, 31
	v_lshl_add_u64 v[6:7], v[2:3], 0, s[66:67]
	v_lshl_add_u64 v[6:7], v[6:7], 2, s[50:51]
	v_mul_f32_e32 v18, v18, v119
.LBB0_171:
	s_and_b64 vcc, exec, s[40:41]
	ds_write_b32 v4, v18 offset:39064
	s_cbranch_vccnz .LBB0_173
	s_ashr_i32 s67, s66, 31
	v_lshl_add_u64 v[6:7], v[2:3], 0, s[66:67]
	v_lshl_add_u64 v[6:7], v[6:7], 2, s[50:51]
	v_mul_f32_e32 v21, v21, v120
.LBB0_173:
	s_and_b64 vcc, exec, s[40:41]
	ds_write_b32 v4, v21 offset:41120
	s_cbranch_vccnz .LBB0_175
	s_ashr_i32 s67, s66, 31
	v_lshl_add_u64 v[6:7], v[2:3], 0, s[66:67]
	v_lshl_add_u64 v[6:7], v[6:7], 2, s[50:51]
	v_mul_f32_e32 v16, v16, v121
.LBB0_175:
	s_and_b64 vcc, exec, s[40:41]
	ds_write_b32 v4, v16 offset:43176
	s_cbranch_vccnz .LBB0_177
	s_ashr_i32 s67, s66, 31
	v_lshl_add_u64 v[6:7], v[2:3], 0, s[66:67]
	v_lshl_add_u64 v[6:7], v[6:7], 2, s[50:51]
	v_mul_f32_e32 v19, v19, v122
.LBB0_177:
	s_and_b64 vcc, exec, s[40:41]
	ds_write_b32 v4, v19 offset:45232
	s_cbranch_vccnz .LBB0_179
	s_ashr_i32 s67, s66, 31
	v_lshl_add_u64 v[6:7], v[2:3], 0, s[66:67]
	v_lshl_add_u64 v[6:7], v[6:7], 2, s[50:51]
	v_mul_f32_e32 v14, v14, v123
.LBB0_179:
	s_and_b64 vcc, exec, s[40:41]
	ds_write_b32 v4, v14 offset:47288
	s_cbranch_vccnz .LBB0_181
	s_ashr_i32 s67, s66, 31
	v_lshl_add_u64 v[6:7], v[2:3], 0, s[66:67]
	v_lshl_add_u64 v[6:7], v[6:7], 2, s[50:51]
	v_mul_f32_e32 v17, v17, v124
.LBB0_181:
	s_and_b64 vcc, exec, s[40:41]
	ds_write_b32 v4, v17 offset:49344
	s_cbranch_vccnz .LBB0_183
	s_ashr_i32 s67, s66, 31
	v_lshl_add_u64 v[6:7], v[2:3], 0, s[66:67]
	v_lshl_add_u64 v[6:7], v[6:7], 2, s[50:51]
	v_mul_f32_e32 v12, v12, v125
.LBB0_183:
	s_and_b64 vcc, exec, s[40:41]
	ds_write_b32 v4, v12 offset:51400
	s_cbranch_vccnz .LBB0_185
	s_ashr_i32 s67, s66, 31
	v_lshl_add_u64 v[6:7], v[2:3], 0, s[66:67]
	v_lshl_add_u64 v[6:7], v[6:7], 2, s[50:51]
	v_mul_f32_e32 v15, v15, v126
.LBB0_185:
	s_and_b64 vcc, exec, s[40:41]
	ds_write_b32 v4, v15 offset:53456
	s_cbranch_vccnz .LBB0_187
	s_ashr_i32 s67, s66, 31
	v_lshl_add_u64 v[6:7], v[2:3], 0, s[66:67]
	v_lshl_add_u64 v[6:7], v[6:7], 2, s[50:51]
	v_mul_f32_e32 v10, v10, v127
.LBB0_187:
	s_and_b64 vcc, exec, s[40:41]
	ds_write_b32 v4, v10 offset:55512
	s_cbranch_vccnz .LBB0_189
	s_ashr_i32 s67, s66, 31
	v_lshl_add_u64 v[6:7], v[2:3], 0, s[66:67]
	v_lshl_add_u64 v[6:7], v[6:7], 2, s[50:51]
	v_mul_f32_e32 v13, v13, v128
.LBB0_189:
	s_and_b64 vcc, exec, s[40:41]
	ds_write_b32 v4, v13 offset:57568
	s_cbranch_vccnz .LBB0_191
	s_ashr_i32 s67, s66, 31
	v_lshl_add_u64 v[6:7], v[2:3], 0, s[66:67]
	v_lshl_add_u64 v[6:7], v[6:7], 2, s[50:51]
	v_mul_f32_e32 v9, v9, v129
.LBB0_191:
	s_and_b64 vcc, exec, s[40:41]
	ds_write_b32 v4, v9 offset:59624
	s_cbranch_vccnz .LBB0_193
	s_ashr_i32 s67, s66, 31
	v_lshl_add_u64 v[6:7], v[2:3], 0, s[66:67]
	v_lshl_add_u64 v[6:7], v[6:7], 2, s[50:51]
	v_mul_f32_e32 v11, v11, v130
.LBB0_193:
	v_readlane_b32 s4, v252, 33
	v_readlane_b32 s5, v252, 34
	s_and_b64 vcc, exec, s[4:5]
	ds_write_b32 v4, v11 offset:61680
	s_cbranch_vccz .LBB0_284
	s_ashr_i32 s67, s66, 31
	v_lshl_add_u64 v[2:3], v[2:3], 0, s[66:67]
	v_lshl_add_u64 v[2:3], v[2:3], 2, s[50:51]
	v_mul_f32_e32 v2, v0, v131
	s_cbranch_execnz .LBB0_196

; DI void convert_tile(const CvtJob& jb, int ti, char* lds) {
;     ...
; #pragma unroll
;   for (int i = 0; i < 32; ++i) v[i] = (n < N) ? jb.src[(size_t)(k0 + kr + 2 * i) * N + n] : 0.f;
; #pragma unroll
;   for (int i = 0; i < 32; ++i) { const int k = kr + 2 * i; tile[k * 257 + nn] = jb.kscale ? v[i] * jb.kscale[k0 + k] : v[i]; }
.LBB0_660:
	v_lshl_add_u32 v4, v3, 2, 0
	s_movk_i32 s4, 0x404
	v_mad_i32_i24 v3, v2, s4, v4
	s_sub_i32 s54, s37, s54
	s_waitcnt vmcnt(0)
	ds_write_b32 v3, v39
	s_and_b64 vcc, exec, s[40:41]
	v_ashrrev_i32_e32 v3, 31, v2
	s_cbranch_vccnz .LBB0_662
	s_ashr_i32 s55, s54, 31
	v_lshl_add_u64 v[6:7], v[2:3], 0, s[54:55]
	v_lshl_add_u64 v[6:7], v[6:7], 2, s[50:51]
	v_mul_f32_e32 v36, v36, v101
.LBB0_662:
	v_mul_i32_i24_e32 v5, 0x404, v2
	v_add_u32_e32 v4, v5, v4
	s_and_b64 vcc, exec, s[40:41]
	ds_write_b32 v4, v36 offset:2056
	s_cbranch_vccnz .LBB0_664
	s_ashr_i32 s55, s54, 31
	v_lshl_add_u64 v[6:7], v[2:3], 0, s[54:55]
	v_lshl_add_u64 v[6:7], v[6:7], 2, s[50:51]
	v_mul_f32_e32 v38, v38, v102
.LBB0_664:
	s_and_b64 vcc, exec, s[40:41]
	ds_write_b32 v4, v38 offset:4112
	s_cbranch_vccnz .LBB0_666
	s_ashr_i32 s55, s54, 31
	v_lshl_add_u64 v[6:7], v[2:3], 0, s[54:55]
	v_lshl_add_u64 v[6:7], v[6:7], 2, s[50:51]
	v_mul_f32_e32 v34, v34, v103
.LBB0_666:
	s_and_b64 vcc, exec, s[40:41]
	ds_write_b32 v4, v34 offset:6168
	s_cbranch_vccnz .LBB0_668
	s_ashr_i32 s55, s54, 31
	v_lshl_add_u64 v[6:7], v[2:3], 0, s[54:55]
	v_lshl_add_u64 v[6:7], v[6:7], 2, s[50:51]
	v_mul_f32_e32 v37, v37, v104
.LBB0_668:
	s_and_b64 vcc, exec, s[40:41]
	ds_write_b32 v4, v37 offset:8224
	s_cbranch_vccnz .LBB0_670
	s_ashr_i32 s55, s54, 31
	v_lshl_add_u64 v[6:7], v[2:3], 0, s[54:55]
	v_lshl_add_u64 v[6:7], v[6:7], 2, s[50:51]
	v_mul_f32_e32 v32, v32, v105
.LBB0_670:
	s_and_b64 vcc, exec, s[40:41]
	ds_write_b32 v4, v32 offset:10280
	s_cbranch_vccnz .LBB0_672
	s_ashr_i32 s55, s54, 31
	v_lshl_add_u64 v[6:7], v[2:3], 0, s[54:55]
	v_lshl_add_u64 v[6:7], v[6:7], 2, s[50:51]
	v_mul_f32_e32 v35, v35, v106
.LBB0_672:
	s_and_b64 vcc, exec, s[40:41]
	ds_write_b32 v4, v35 offset:12336
	s_cbranch_vccnz .LBB0_674
	s_ashr_i32 s55, s54, 31
	v_lshl_add_u64 v[6:7], v[2:3], 0, s[54:55]
	v_lshl_add_u64 v[6:7], v[6:7], 2, s[50:51]
	v_mul_f32_e32 v30, v30, v107
.LBB0_674:
	s_and_b64 vcc, exec, s[40:41]
	ds_write_b32 v4, v30 offset:14392
	s_cbranch_vccnz .LBB0_676
	s_ashr_i32 s55, s54, 31
	v_lshl_add_u64 v[6:7], v[2:3], 0, s[54:55]
	v_lshl_add_u64 v[6:7], v[6:7], 2, s[50:51]
	v_mul_f32_e32 v33, v33, v108
.LBB0_676:
	s_and_b64 vcc, exec, s[40:41]
	ds_write_b32 v4, v33 offset:16448
	s_cbranch_vccnz .LBB0_678
	s_ashr_i32 s55, s54, 31
	v_lshl_add_u64 v[6:7], v[2:3], 0, s[54:55]
	v_lshl_add_u64 v[6:7], v[6:7], 2, s[50:51]
	v_mul_f32_e32 v28, v28, v109
.LBB0_678:
	s_and_b64 vcc, exec, s[40:41]
	ds_write_b32 v4, v28 offset:18504
	s_cbranch_vccnz .LBB0_680
	s_ashr_i32 s55, s54, 31
	v_lshl_add_u64 v[6:7], v[2:3], 0, s[54:55]
	v_lshl_add_u64 v[6:7], v[6:7], 2, s[50:51]
	v_mul_f32_e32 v31, v31, v110
.LBB0_680:
	s_and_b64 vcc, exec, s[40:41]
	ds_write_b32 v4, v31 offset:20560
	s_cbranch_vccnz .LBB0_682
	s_ashr_i32 s55, s54, 31
	v_lshl_add_u64 v[6:7], v[2:3], 0, s[54:55]
	v_lshl_add_u64 v[6:7], v[6:7], 2, s[50:51]
	v_mul_f32_e32 v26, v26, v111
.LBB0_682:
	s_and_b64 vcc, exec, s[40:41]
	ds_write_b32 v4, v26 offset:22616
	s_cbranch_vccnz .LBB0_684
	s_ashr_i32 s55, s54, 31
	v_lshl_add_u64 v[6:7], v[2:3], 0, s[54:55]
	v_lshl_add_u64 v[6:7], v[6:7], 2, s[50:51]
	v_mul_f32_e32 v29, v29, v112
.LBB0_684:
	s_and_b64 vcc, exec, s[40:41]
	ds_write_b32 v4, v29 offset:24672
	s_cbranch_vccnz .LBB0_686
	s_ashr_i32 s55, s54, 31
	v_lshl_add_u64 v[6:7], v[2:3], 0, s[54:55]
	v_lshl_add_u64 v[6:7], v[6:7], 2, s[50:51]
	v_mul_f32_e32 v24, v24, v113
.LBB0_686:
	s_and_b64 vcc, exec, s[40:41]
	ds_write_b32 v4, v24 offset:26728
	s_cbranch_vccnz .LBB0_688
	s_ashr_i32 s55, s54, 31
	v_lshl_add_u64 v[6:7], v[2:3], 0, s[54:55]
	v_lshl_add_u64 v[6:7], v[6:7], 2, s[50:51]
	v_mul_f32_e32 v27, v27, v114
.LBB0_688:
	s_and_b64 vcc, exec, s[40:41]
	ds_write_b32 v4, v27 offset:28784
	s_cbranch_vccnz .LBB0_690
	s_ashr_i32 s55, s54, 31
	v_lshl_add_u64 v[6:7], v[2:3], 0, s[54:55]
	v_lshl_add_u64 v[6:7], v[6:7], 2, s[50:51]
	v_mul_f32_e32 v22, v22, v115
; DI void convert_tile(const CvtJob& jb, int ti, char* lds) {
;     ...
; #pragma unroll
;   for (int i = 0; i < 32; ++i) v[i] = (n < N) ? jb.src[(size_t)(k0 + kr + 2 * i) * N + n] : 0.f;
; #pragma unroll
;   for (int i = 0; i < 32; ++i) { const int k = kr + 2 * i; tile[k * 257 + nn] = jb.kscale ? v[i] * jb.kscale[k0 + k] : v[i]; }
.LBB0_690:
	s_and_b64 vcc, exec, s[40:41]
	ds_write_b32 v4, v22 offset:30840
	s_cbranch_vccnz .LBB0_692
	s_ashr_i32 s55, s54, 31
	v_lshl_add_u64 v[6:7], v[2:3], 0, s[54:55]
	v_lshl_add_u64 v[6:7], v[6:7], 2, s[50:51]
	v_mul_f32_e32 v25, v25, v116
.LBB0_692:
	s_and_b64 vcc, exec, s[40:41]
	ds_write_b32 v4, v25 offset:32896
	s_cbranch_vccnz .LBB0_694
	s_ashr_i32 s55, s54, 31
	v_lshl_add_u64 v[6:7], v[2:3], 0, s[54:55]
	v_lshl_add_u64 v[6:7], v[6:7], 2, s[50:51]
	v_mul_f32_e32 v20, v20, v117
.LBB0_694:
	s_and_b64 vcc, exec, s[40:41]
	ds_write_b32 v4, v20 offset:34952
	s_cbranch_vccnz .LBB0_696
	s_ashr_i32 s55, s54, 31
	v_lshl_add_u64 v[6:7], v[2:3], 0, s[54:55]
	v_lshl_add_u64 v[6:7], v[6:7], 2, s[50:51]
	v_mul_f32_e32 v23, v23, v118
.LBB0_696:
	s_and_b64 vcc, exec, s[40:41]
	ds_write_b32 v4, v23 offset:37008
	s_cbranch_vccnz .LBB0_698
	s_ashr_i32 s55, s54, 31
	v_lshl_add_u64 v[6:7], v[2:3], 0, s[54:55]
	v_lshl_add_u64 v[6:7], v[6:7], 2, s[50:51]
	v_mul_f32_e32 v18, v18, v119
.LBB0_698:
	s_and_b64 vcc, exec, s[40:41]
	ds_write_b32 v4, v18 offset:39064
	s_cbranch_vccnz .LBB0_700
	s_ashr_i32 s55, s54, 31
	v_lshl_add_u64 v[6:7], v[2:3], 0, s[54:55]
	v_lshl_add_u64 v[6:7], v[6:7], 2, s[50:51]
	v_mul_f32_e32 v21, v21, v120
.LBB0_700:
	s_and_b64 vcc, exec, s[40:41]
	ds_write_b32 v4, v21 offset:41120
	s_cbranch_vccnz .LBB0_702
	s_ashr_i32 s55, s54, 31
	v_lshl_add_u64 v[6:7], v[2:3], 0, s[54:55]
	v_lshl_add_u64 v[6:7], v[6:7], 2, s[50:51]
	v_mul_f32_e32 v16, v16, v121
.LBB0_702:
	s_and_b64 vcc, exec, s[40:41]
	ds_write_b32 v4, v16 offset:43176
	s_cbranch_vccnz .LBB0_704
	s_ashr_i32 s55, s54, 31
	v_lshl_add_u64 v[6:7], v[2:3], 0, s[54:55]
	v_lshl_add_u64 v[6:7], v[6:7], 2, s[50:51]
	v_mul_f32_e32 v19, v19, v122
.LBB0_704:
	s_and_b64 vcc, exec, s[40:41]
	ds_write_b32 v4, v19 offset:45232
	s_cbranch_vccnz .LBB0_706
	s_ashr_i32 s55, s54, 31
	v_lshl_add_u64 v[6:7], v[2:3], 0, s[54:55]
	v_lshl_add_u64 v[6:7], v[6:7], 2, s[50:51]
	v_mul_f32_e32 v14, v14, v123
.LBB0_706:
	s_and_b64 vcc, exec, s[40:41]
	ds_write_b32 v4, v14 offset:47288
	s_cbranch_vccnz .LBB0_708
	s_ashr_i32 s55, s54, 31
	v_lshl_add_u64 v[6:7], v[2:3], 0, s[54:55]
	v_lshl_add_u64 v[6:7], v[6:7], 2, s[50:51]
	v_mul_f32_e32 v17, v17, v124
.LBB0_708:
	s_and_b64 vcc, exec, s[40:41]
	ds_write_b32 v4, v17 offset:49344
	s_cbranch_vccnz .LBB0_710
	s_ashr_i32 s55, s54, 31
	v_lshl_add_u64 v[6:7], v[2:3], 0, s[54:55]
	v_lshl_add_u64 v[6:7], v[6:7], 2, s[50:51]
	v_mul_f32_e32 v12, v12, v125
.LBB0_710:
	s_and_b64 vcc, exec, s[40:41]
	ds_write_b32 v4, v12 offset:51400
	s_cbranch_vccnz .LBB0_712
	s_ashr_i32 s55, s54, 31
	v_lshl_add_u64 v[6:7], v[2:3], 0, s[54:55]
	v_lshl_add_u64 v[6:7], v[6:7], 2, s[50:51]
	v_mul_f32_e32 v15, v15, v126
.LBB0_712:
	s_and_b64 vcc, exec, s[40:41]
	ds_write_b32 v4, v15 offset:53456
	s_cbranch_vccnz .LBB0_714
	s_ashr_i32 s55, s54, 31
	v_lshl_add_u64 v[6:7], v[2:3], 0, s[54:55]
	v_lshl_add_u64 v[6:7], v[6:7], 2, s[50:51]
	v_mul_f32_e32 v10, v10, v127
.LBB0_714:
	s_and_b64 vcc, exec, s[40:41]
	ds_write_b32 v4, v10 offset:55512
	s_cbranch_vccnz .LBB0_716
	s_ashr_i32 s55, s54, 31
	v_lshl_add_u64 v[6:7], v[2:3], 0, s[54:55]
	v_lshl_add_u64 v[6:7], v[6:7], 2, s[50:51]
	v_mul_f32_e32 v13, v13, v128
.LBB0_716:
	s_and_b64 vcc, exec, s[40:41]
	ds_write_b32 v4, v13 offset:57568
	s_cbranch_vccnz .LBB0_718
	s_ashr_i32 s55, s54, 31
	v_lshl_add_u64 v[6:7], v[2:3], 0, s[54:55]
	v_lshl_add_u64 v[6:7], v[6:7], 2, s[50:51]
	v_mul_f32_e32 v9, v9, v129
.LBB0_718:
	s_and_b64 vcc, exec, s[40:41]
	ds_write_b32 v4, v9 offset:59624
	s_cbranch_vccnz .LBB0_720
	s_ashr_i32 s55, s54, 31
	v_lshl_add_u64 v[6:7], v[2:3], 0, s[54:55]
	v_lshl_add_u64 v[6:7], v[6:7], 2, s[50:51]
	v_mul_f32_e32 v11, v11, v130
.LBB0_720:
	v_readlane_b32 s4, v252, 33
	v_readlane_b32 s5, v252, 34
	s_and_b64 vcc, exec, s[4:5]
	ds_write_b32 v4, v11 offset:61680
	s_cbranch_vccz .LBB0_807
	s_ashr_i32 s55, s54, 31
	v_lshl_add_u64 v[2:3], v[2:3], 0, s[54:55]
	v_lshl_add_u64 v[2:3], v[2:3], 2, s[50:51]
	v_mul_f32_e32 v2, v0, v131
	s_cbranch_execnz .LBB0_723

; #define MFMA(a, b, c) __builtin_amdgcn_mfma_f32_32x32x16_bf16((a), (b), (c), 0, 0, 0)
; DI void ssd_scan_phase(bf16_t* P, const bf16_t* BT, const bf16_t* Cc, const bf16_t* CB, const float* dt, const float* acs,
;                        const float* cw, const float* cb, const float* Dp, char* lds, bool dry, int mode, float* Sbuf) {
;     ...
;         const int lt = wave;
;         f32x16 ad, ao;
; #pragma unroll
;         for (int i = 0; i < 16; ++i) { ad[i] = 0.f; ao[i] = 0.f; }
;         const char* stb = sSt + (c & 1) * 8192;
; #pragma unroll
;         for (int kk = 0; kk < 8; ++kk) {
;           const bf16x8 yf = *(const bf16x8*)(sCBL + swz128(32 * lt + lq, 2 * kk + hq));
;           const bf16x8 xf = *(const bf16x8*)(sXdt + swz128(lq, 2 * kk + hq));
;           ad = MFMA(xf, yf, ad);
;           const bf16x8 yf2 = *(const bf16x8*)(sC + swz128(32 * lt + lq, 2 * kk + hq));
;           const bf16x8 xf2 = *(const bf16x8*)(stb + swz128(lq, 2 * kk + hq));
;           ao = MFMA(xf2, yf2, ao);
;         }
;         const int l = 32 * lt + l31;
;         const float eo = __expf(cAcs[l]);
.LBB0_1101:
	s_waitcnt lgkmcnt(0)
	s_barrier
	v_mov_b32_e32 v197, v133
	v_mov_b32_e32 v174, v175
	s_and_saveexec_b64 s[80:81], s[40:41]
	s_xor_b64 s[80:81], exec, s[80:81]
	s_cbranch_execz .LBB0_1107
	s_and_b64 vcc, exec, s[56:57]
	s_cbranch_vccnz .LBB0_1106
	s_andn2_b64 vcc, exec, s[82:83]
	v_bitop3_b32 v20, v174, v197, 15 bitop3:0x6c
	v_lshlrev_b32_e32 v199, 8, v174
	v_lshlrev_b32_e32 v24, 4, v20
	v_add_lshl_u32 v198, v174, v183, 8
	s_add_i32 s91, 0, 0x18000
	s_lshl_b32 s90, s90, 13
	s_add_i32 s90, s90, 0
	s_add_i32 s90, s90, 0x1c000
	v_add_u32_e32 v250, v24, v198
	v_add_u32_e32 v251, v24, v199
	v_add_u32_e32 v230, s90, v251
	v_add_u32_e32 v251, s91, v251
	ds_read_b128 v[20:23], v250
	ds_read_b128 v[24:27], v251
	ds_read_b128 v[36:39], v250 offset:32768
	ds_read_b128 v[40:43], v230
	v_xor_b32_e32 v231, 0x20, v250
	ds_read_b128 v[222:225], v231
	v_xor_b32_e32 v231, 0x20, v251
	ds_read_b128 v[226:229], v231
	v_xor_b32_e32 v231, 0x20, v250
	ds_read_b128 v[234:237], v231 offset:32768
	v_xor_b32_e32 v231, 0x20, v230
	ds_read_b128 v[238:241], v231
	v_xor_b32_e32 v231, 0x40, v250
	ds_read_b128 v[242:245], v231
	v_xor_b32_e32 v231, 0x40, v251
	ds_read_b128 v[246:249], v231
	s_waitcnt lgkmcnt(8)
	v_mfma_f32_32x32x16_bf16 v[20:35], v[24:27], v[20:23], 0
	s_waitcnt lgkmcnt(6)
	v_mfma_f32_32x32x16_bf16 v[36:51], v[40:43], v[36:39], 0
	s_waitcnt lgkmcnt(4)
	v_mfma_f32_32x32x16_bf16 v[20:35], v[226:229], v[222:225], v[20:35]
	v_xor_b32_e32 v231, 0x40, v250
	ds_read_b128 v[222:225], v231 offset:32768
	v_xor_b32_e32 v231, 0x40, v230
	ds_read_b128 v[226:229], v231
	s_waitcnt lgkmcnt(4)
	v_mfma_f32_32x32x16_bf16 v[36:51], v[238:241], v[234:237], v[36:51]
	v_xor_b32_e32 v231, 0x60, v250
	ds_read_b128 v[234:237], v231
	v_xor_b32_e32 v231, 0x60, v251
	ds_read_b128 v[238:241], v231
	s_waitcnt lgkmcnt(4)
	v_mfma_f32_32x32x16_bf16 v[20:35], v[246:249], v[242:245], v[20:35]
	v_xor_b32_e32 v231, 0x60, v250
	ds_read_b128 v[242:245], v231 offset:32768
	v_xor_b32_e32 v231, 0x60, v230
	ds_read_b128 v[246:249], v231
	s_waitcnt lgkmcnt(4)
	v_mfma_f32_32x32x16_bf16 v[36:51], v[226:229], v[222:225], v[36:51]
	v_xor_b32_e32 v231, 0x80, v250
	ds_read_b128 v[222:225], v231
	v_xor_b32_e32 v231, 0x80, v251
	ds_read_b128 v[226:229], v231
	s_waitcnt lgkmcnt(4)
	v_mfma_f32_32x32x16_bf16 v[20:35], v[238:241], v[234:237], v[20:35]
	v_xor_b32_e32 v231, 0x80, v250
	ds_read_b128 v[234:237], v231 offset:32768
	v_xor_b32_e32 v231, 0x80, v230
	ds_read_b128 v[238:241], v231
	s_waitcnt lgkmcnt(4)
	v_mfma_f32_32x32x16_bf16 v[36:51], v[246:249], v[242:245], v[36:51]
	v_xor_b32_e32 v231, 0xa0, v250
	ds_read_b128 v[242:245], v231
	v_xor_b32_e32 v231, 0xa0, v251
	ds_read_b128 v[246:249], v231
	s_waitcnt lgkmcnt(4)
	v_mfma_f32_32x32x16_bf16 v[20:35], v[226:229], v[222:225], v[20:35]
	v_xor_b32_e32 v231, 0xa0, v250
	ds_read_b128 v[222:225], v231 offset:32768
	v_xor_b32_e32 v231, 0xa0, v230
	ds_read_b128 v[226:229], v231
	s_waitcnt lgkmcnt(4)
	v_mfma_f32_32x32x16_bf16 v[36:51], v[238:241], v[234:237], v[36:51]
	v_xor_b32_e32 v231, 0xc0, v250
	ds_read_b128 v[234:237], v231
	v_xor_b32_e32 v231, 0xc0, v251
	ds_read_b128 v[238:241], v231
	s_waitcnt lgkmcnt(4)
	v_mfma_f32_32x32x16_bf16 v[20:35], v[246:249], v[242:245], v[20:35]
	v_xor_b32_e32 v231, 0xc0, v250
	ds_read_b128 v[242:245], v231 offset:32768
	v_xor_b32_e32 v231, 0xc0, v230
	ds_read_b128 v[246:249], v231
	s_waitcnt lgkmcnt(4)
	v_mfma_f32_32x32x16_bf16 v[36:51], v[226:229], v[222:225], v[36:51]
	v_xor_b32_e32 v231, 0xe0, v250
	ds_read_b128 v[222:225], v231
	v_xor_b32_e32 v231, 0xe0, v251
	ds_read_b128 v[226:229], v231
	s_waitcnt lgkmcnt(4)
	v_mfma_f32_32x32x16_bf16 v[20:35], v[238:241], v[234:237], v[20:35]
	v_xor_b32_e32 v231, 0xe0, v250
	ds_read_b128 v[234:237], v231 offset:32768
	v_xor_b32_e32 v231, 0xe0, v230
	ds_read_b128 v[238:241], v231
	v_lshl_add_u32 v174, v187, 2, s88
	ds_read_b32 v174, v174
	v_mov_b64_e32 v[198:199], s[72:73]
	v_mad_u64_u32 v[198:199], s[90:91], v172, s96, v[198:199]
	v_mad_i32_i24 v199, v173, s96, v199
	v_lshl_add_u64 v[172:173], v[198:199], 0, v[0:1]
	s_waitcnt lgkmcnt(5)
	v_mfma_f32_32x32x16_bf16 v[36:51], v[246:249], v[242:245], v[36:51]
	s_waitcnt lgkmcnt(3)
	v_mfma_f32_32x32x16_bf16 v[20:35], v[226:229], v[222:225], v[20:35]
	s_waitcnt lgkmcnt(0)
	v_mul_f32_e32 v174, 0x3fb8aa3b, v174
	v_mfma_f32_32x32x16_bf16 v[36:51], v[238:241], v[234:237], v[36:51]
	v_exp_f32_e32 v174, v174
	v_lshlrev_b32_e32 v226, 16, v158
	v_and_b32_e32 v227, 0xffff0000, v158
	v_mul_f32_e32 v197, 0xbfb8aa3b, v226
	v_exp_f32_e32 v197, v197
	ds_read2_b64 v[222:225], v193 offset1:2
	s_nop 5
	v_pk_fma_f32 v[20:21], v[36:37], v[174:175], v[20:21] op_sel_hi:[1,0,1]
	v_mul_f32_e32 v36, 0xbfb8aa3b, v227
	v_exp_f32_e32 v36, v36
	v_add_f32_e32 v197, 1.0, v197
	v_rcp_f32_e32 v228, v197
	s_waitcnt lgkmcnt(0)
; DI unsigned pk2(float lo, float hi) { f32x2 v = {lo, hi}; bf2_t r = __builtin_convertvector(v, bf2_t); return __builtin_bit_cast(unsigned, r); }
; DI float bflo(unsigned u) { return __uint_as_float(u << 16); }
; DI float bfhi(unsigned u) { return __uint_as_float(u & 0xffff0000u); }
; DI float silu(float x) { return x * __builtin_amdgcn_rcpf(1.f + __expf(-x)); }
; DI void ssd_scan_phase(bf16_t* P, const bf16_t* BT, const bf16_t* Cc, const bf16_t* CB, const float* dt, const float* acs,
;                        const float* cw, const float* cb, const float* Dp, char* lds, bool dry, int mode, float* Sbuf) {
;     ...
;         const int l = 32 * lt + l31;
;         const float eo = __expf(cAcs[l]);
;         bf16_t* Zq = P + t0 * 5120 + pcol;
; #pragma unroll
;         for (int gi = 0; gi < 4; ++gi) {
;           const int p0 = 8 * gi + 4 * h;
;           const u32x2 xsv = *(const u32x2*)(sXs + l * 80 + p0 * 2);
;           const u32x2 zv = cz[gi];
;           const float xs0 = bflo(xsv[0]), xs1 = bfhi(xsv[0]), xs2 = bflo(xsv[1]), xs3 = bfhi(xsv[1]);
;           const float z0 = bflo(zv[0]), z1 = bfhi(zv[0]), z2 = bflo(zv[1]), z3 = bfhi(zv[1]);
;           const float y0 = (ad[4 * gi] + eo * ao[4 * gi] + Dh * xs0) * silu(z0);
;           const float y1 = (ad[4 * gi + 1] + eo * ao[4 * gi + 1] + Dh * xs1) * silu(z1);
;           const float y2 = (ad[4 * gi + 2] + eo * ao[4 * gi + 2] + Dh * xs2) * silu(z2);
;           const float y3 = (ad[4 * gi + 3] + eo * ao[4 * gi + 3] + Dh * xs3) * silu(z3);
;           u32x2 ov; ov[0] = pk2(y0, y1); ov[1] = pk2(y2, y3);
;           if (!dry) *(u32x2*)(Zq + zoff + 8 * gi) = ov;
;         }
;         if (c + 1 < c1) {
; #pragma unroll
;           for (int gi = 0; gi < 4; ++gi) cz[gi] = *(const u32x2*)(Zq + 128 * 5120 + zoff + 8 * gi);
;         }
	v_lshlrev_b32_e32 v198, 16, v222
	v_add_f32_e32 v36, 1.0, v36
	v_rcp_f32_e32 v229, v36
	v_and_b32_e32 v199, 0xffff0000, v222
	v_pk_fma_f32 v[20:21], v[156:157], v[198:199], v[20:21]
	v_lshlrev_b32_e32 v198, 16, v159
	v_pk_mul_f32 v[36:37], v[228:229], v[226:227]
	v_and_b32_e32 v199, 0xffff0000, v159
	v_pk_mul_f32 v[20:21], v[36:37], v[20:21]
	v_lshlrev_b32_e32 v36, 16, v223
	v_and_b32_e32 v37, 0xffff0000, v223
	v_pk_fma_f32 v[22:23], v[38:39], v[174:175], v[22:23] op_sel_hi:[1,0,1]
	v_mul_f32_e32 v197, 0xbfb8aa3b, v198
	v_pk_fma_f32 v[22:23], v[156:157], v[36:37], v[22:23]
	v_mul_f32_e32 v36, 0xbfb8aa3b, v199
	v_exp_f32_e32 v197, v197
	v_exp_f32_e32 v36, v36
	v_lshlrev_b32_e32 v38, 16, v160
	v_and_b32_e32 v39, 0xffff0000, v160
	v_add_f32_e32 v197, 1.0, v197
	v_add_f32_e32 v36, 1.0, v36
	v_rcp_f32_e32 v222, v197
	v_rcp_f32_e32 v223, v36
	v_pk_fma_f32 v[24:25], v[40:41], v[174:175], v[24:25] op_sel_hi:[1,0,1]
	v_mul_f32_e32 v197, 0xbfb8aa3b, v38
	v_exp_f32_e32 v197, v197
	v_pk_mul_f32 v[36:37], v[222:223], v[198:199]
	v_pk_fma_f32 v[26:27], v[42:43], v[174:175], v[26:27] op_sel_hi:[1,0,1]
	v_pk_mul_f32 v[22:23], v[36:37], v[22:23]
	v_lshlrev_b32_e32 v36, 16, v224
	v_and_b32_e32 v37, 0xffff0000, v224
	v_pk_fma_f32 v[24:25], v[156:157], v[36:37], v[24:25]
	v_mul_f32_e32 v36, 0xbfb8aa3b, v39
	v_exp_f32_e32 v36, v36
	v_add_f32_e32 v197, 1.0, v197
	v_rcp_f32_e32 v198, v197
	v_cvt_pk_bf16_f32 v20, v20, v21
	v_add_f32_e32 v36, 1.0, v36
	v_rcp_f32_e32 v199, v36
	v_cvt_pk_bf16_f32 v21, v22, v23
	global_store_dwordx2 v[172:173], v[20:21], off
	ds_read2_b64 v[20:23], v193 offset0:4 offset1:6
	v_pk_mul_f32 v[36:37], v[198:199], v[38:39]
	v_lshlrev_b32_e32 v38, 16, v161
	v_pk_mul_f32 v[24:25], v[36:37], v[24:25]
	v_lshlrev_b32_e32 v36, 16, v225
	v_and_b32_e32 v37, 0xffff0000, v225
	v_and_b32_e32 v39, 0xffff0000, v161
	v_mul_f32_e32 v40, 0xbfb8aa3b, v38
	v_pk_fma_f32 v[26:27], v[156:157], v[36:37], v[26:27]
	v_mul_f32_e32 v36, 0xbfb8aa3b, v39
	v_exp_f32_e32 v40, v40
	v_exp_f32_e32 v36, v36
	v_cvt_pk_bf16_f32 v24, v24, v25
	v_pk_fma_f32 v[28:29], v[44:45], v[174:175], v[28:29] op_sel_hi:[1,0,1]
	v_add_f32_e32 v40, 1.0, v40
	v_add_f32_e32 v36, 1.0, v36
	v_rcp_f32_e32 v40, v40
	v_rcp_f32_e32 v41, v36
	v_pk_fma_f32 v[30:31], v[46:47], v[174:175], v[30:31] op_sel_hi:[1,0,1]
	v_pk_mul_f32 v[36:37], v[40:41], v[38:39]
	s_nop 0
	v_pk_mul_f32 v[26:27], v[36:37], v[26:27]
	s_nop 0
	v_cvt_pk_bf16_f32 v25, v26, v27
	v_lshlrev_b32_e32 v26, 16, v162
	global_store_dwordx2 v[172:173], v[24:25], off offset:16
	s_waitcnt lgkmcnt(0)
	v_lshlrev_b32_e32 v24, 16, v20
	v_and_b32_e32 v25, 0xffff0000, v20
	v_mul_f32_e32 v20, 0xbfb8aa3b, v26
	v_exp_f32_e32 v20, v20
	v_and_b32_e32 v27, 0xffff0000, v162
	v_pk_fma_f32 v[24:25], v[156:157], v[24:25], v[28:29]
	v_add_f32_e32 v20, 1.0, v20
	v_rcp_f32_e32 v36, v20
	v_mul_f32_e32 v20, 0xbfb8aa3b, v27
	v_exp_f32_e32 v20, v20
	s_nop 0
	v_add_f32_e32 v20, 1.0, v20
	v_rcp_f32_e32 v37, v20
	v_lshlrev_b32_e32 v20, 16, v21
	v_and_b32_e32 v21, 0xffff0000, v21
	v_pk_fma_f32 v[20:21], v[156:157], v[20:21], v[30:31]
	v_pk_mul_f32 v[26:27], v[36:37], v[26:27]
	s_nop 0
	v_pk_mul_f32 v[24:25], v[26:27], v[24:25]
	v_lshlrev_b32_e32 v26, 16, v163
	v_and_b32_e32 v27, 0xffff0000, v163
	v_mul_f32_e32 v28, 0xbfb8aa3b, v26
	v_mul_f32_e32 v29, 0xbfb8aa3b, v27
	v_exp_f32_e32 v28, v28
	v_exp_f32_e32 v29, v29
	v_cvt_pk_bf16_f32 v24, v24, v25
	v_add_f32_e32 v28, 1.0, v28
	v_add_f32_e32 v29, 1.0, v29
	v_rcp_f32_e32 v28, v28
	v_rcp_f32_e32 v29, v29
	s_nop 0
	v_pk_mul_f32 v[26:27], v[28:29], v[26:27]
	s_nop 0
	v_pk_mul_f32 v[20:21], v[26:27], v[20:21]
	v_pk_fma_f32 v[28:29], v[48:49], v[174:175], v[32:33] op_sel_hi:[1,0,1]
	v_cvt_pk_bf16_f32 v25, v20, v21
	global_store_dwordx2 v[172:173], v[24:25], off offset:32
	s_waitcnt vmcnt(3)
	v_lshlrev_b32_e32 v24, 16, v2
	v_lshlrev_b32_e32 v20, 16, v22
	v_and_b32_e32 v21, 0xffff0000, v22
	v_mul_f32_e32 v22, 0xbfb8aa3b, v24
	v_exp_f32_e32 v22, v22
	v_and_b32_e32 v25, 0xffff0000, v2
	v_pk_fma_f32 v[20:21], v[156:157], v[20:21], v[28:29]
	v_pk_fma_f32 v[28:29], v[50:51], v[174:175], v[34:35] op_sel_hi:[1,0,1]
	v_add_f32_e32 v22, 1.0, v22
	v_rcp_f32_e32 v26, v22
	v_mul_f32_e32 v22, 0xbfb8aa3b, v25
	v_exp_f32_e32 v22, v22
	s_nop 0
	v_add_f32_e32 v22, 1.0, v22
	v_rcp_f32_e32 v27, v22
	v_lshlrev_b32_e32 v22, 16, v23
	v_and_b32_e32 v23, 0xffff0000, v23
	v_pk_fma_f32 v[22:23], v[156:157], v[22:23], v[28:29]
	v_pk_mul_f32 v[24:25], v[26:27], v[24:25]
	s_nop 0
	v_pk_mul_f32 v[20:21], v[24:25], v[20:21]
	v_lshlrev_b32_e32 v24, 16, v3
	v_and_b32_e32 v25, 0xffff0000, v3
	v_mul_f32_e32 v26, 0xbfb8aa3b, v24
	v_mul_f32_e32 v27, 0xbfb8aa3b, v25
	v_exp_f32_e32 v26, v26
	v_exp_f32_e32 v27, v27
	v_cvt_pk_bf16_f32 v20, v20, v21
	v_add_f32_e32 v26, 1.0, v26
	v_add_f32_e32 v27, 1.0, v27
	v_rcp_f32_e32 v26, v26
	v_rcp_f32_e32 v27, v27
	s_nop 0
	v_pk_mul_f32 v[24:25], v[26:27], v[24:25]
	s_nop 0
	v_pk_mul_f32 v[22:23], v[24:25], v[22:23]
	s_nop 0
	v_cvt_pk_bf16_f32 v21, v22, v23
	global_store_dwordx2 v[172:173], v[20:21], off offset:48
	s_cbranch_vccnz .LBB0_1105
	s_mov_b64 s[82:83], 0x140000
	v_add_co_u32_e32 v20, vcc, 0x140000, v172
	v_lshl_add_u64 v[2:3], v[172:173], 0, s[82:83]
	s_nop 0
	v_addc_co_u32_e32 v21, vcc, 0, v173, vcc
	global_load_dwordx2 v[158:159], v[20:21], off
	global_load_dwordx2 v[160:161], v[2:3], off offset:16
	global_load_dwordx2 v[162:163], v[2:3], off offset:32
	s_nop 0
	global_load_dwordx2 v[2:3], v[2:3], off offset:48

; DI void convert_tile(const CvtJob& jb, int ti, char* lds) {
;     ...
; #pragma unroll
;   for (int i = 0; i < 32; ++i) v[i] = (n < N) ? jb.src[(size_t)(k0 + kr + 2 * i) * N + n] : 0.f;
; #pragma unroll
;   for (int i = 0; i < 32; ++i) { const int k = kr + 2 * i; tile[k * 257 + nn] = jb.kscale ? v[i] * jb.kscale[k0 + k] : v[i]; }
.LBB0_1277:
	s_or_b64 exec, exec, s[40:41]
	v_readlane_b32 s4, v253, 50
	v_readlane_b32 s5, v253, 51
	s_andn2_b64 vcc, exec, s[4:5]
	s_nop 0
	v_cndmask_b32_e64 v5, 0, 1, s[4:5]
	v_cmp_ne_u32_e64 s[40:41], 1, v5
	s_cbranch_vccnz .LBB0_1279
	v_ashrrev_i32_e32 v5, 31, v4
	v_lshl_add_u64 v[4:5], v[4:5], 2, s[0:1]
	s_waitcnt vmcnt(24)
	global_load_dword v100, v[4:5], off
	global_load_dword v101, v[4:5], off offset:8
	global_load_dword v102, v[4:5], off offset:16
	global_load_dword v103, v[4:5], off offset:24
	global_load_dword v104, v[4:5], off offset:32
	global_load_dword v105, v[4:5], off offset:40
	global_load_dword v106, v[4:5], off offset:48
	global_load_dword v107, v[4:5], off offset:56
	global_load_dword v108, v[4:5], off offset:64
	global_load_dword v109, v[4:5], off offset:72
	global_load_dword v110, v[4:5], off offset:80
	global_load_dword v111, v[4:5], off offset:88
	global_load_dword v112, v[4:5], off offset:96
	global_load_dword v113, v[4:5], off offset:104
	global_load_dword v114, v[4:5], off offset:112
	global_load_dword v115, v[4:5], off offset:120
	global_load_dword v116, v[4:5], off offset:128
	global_load_dword v117, v[4:5], off offset:136
	global_load_dword v118, v[4:5], off offset:144
	global_load_dword v119, v[4:5], off offset:152
	global_load_dword v120, v[4:5], off offset:160
	global_load_dword v121, v[4:5], off offset:168
	global_load_dword v122, v[4:5], off offset:176
	global_load_dword v123, v[4:5], off offset:184
	global_load_dword v124, v[4:5], off offset:192
	global_load_dword v125, v[4:5], off offset:200
	global_load_dword v126, v[4:5], off offset:208
	global_load_dword v127, v[4:5], off offset:216
	global_load_dword v128, v[4:5], off offset:224
	global_load_dword v129, v[4:5], off offset:232
	global_load_dword v130, v[4:5], off offset:240
	global_load_dword v131, v[4:5], off offset:248
	s_waitcnt vmcnt(0)
	v_mul_f32_e32 v39, v39, v100
.LBB0_1279:
	v_lshl_add_u32 v4, v3, 2, 0
	s_movk_i32 s4, 0x404
	v_mad_i32_i24 v3, v2, s4, v4
	s_sub_i32 s48, s50, s48
	s_waitcnt vmcnt(0)
	ds_write_b32 v3, v39
	s_and_b64 vcc, exec, s[40:41]
	v_ashrrev_i32_e32 v3, 31, v2
	s_cbranch_vccnz .LBB0_1281
	s_ashr_i32 s49, s48, 31
	v_lshl_add_u64 v[6:7], v[2:3], 0, s[48:49]
	v_lshl_add_u64 v[6:7], v[6:7], 2, s[0:1]
	v_mul_f32_e32 v37, v37, v101
.LBB0_1281:
	v_mul_i32_i24_e32 v5, 0x404, v2
	v_add_u32_e32 v4, v5, v4
	s_and_b64 vcc, exec, s[40:41]
	ds_write_b32 v4, v37 offset:2056
	s_cbranch_vccnz .LBB0_1283
	s_ashr_i32 s49, s48, 31
	v_lshl_add_u64 v[6:7], v[2:3], 0, s[48:49]
	v_lshl_add_u64 v[6:7], v[6:7], 2, s[0:1]
	v_mul_f32_e32 v38, v38, v102
.LBB0_1283:
	s_and_b64 vcc, exec, s[40:41]
	ds_write_b32 v4, v38 offset:4112
	s_cbranch_vccnz .LBB0_1285
	s_ashr_i32 s49, s48, 31
	v_lshl_add_u64 v[6:7], v[2:3], 0, s[48:49]
	v_lshl_add_u64 v[6:7], v[6:7], 2, s[0:1]
	v_mul_f32_e32 v35, v35, v103
.LBB0_1285:
	s_and_b64 vcc, exec, s[40:41]
	ds_write_b32 v4, v35 offset:6168
	s_cbranch_vccnz .LBB0_1287
	s_ashr_i32 s49, s48, 31
	v_lshl_add_u64 v[6:7], v[2:3], 0, s[48:49]
	v_lshl_add_u64 v[6:7], v[6:7], 2, s[0:1]
	v_mul_f32_e32 v36, v36, v104
.LBB0_1287:
	s_and_b64 vcc, exec, s[40:41]
	ds_write_b32 v4, v36 offset:8224
	s_cbranch_vccnz .LBB0_1289
	s_ashr_i32 s49, s48, 31
	v_lshl_add_u64 v[6:7], v[2:3], 0, s[48:49]
	v_lshl_add_u64 v[6:7], v[6:7], 2, s[0:1]
	v_mul_f32_e32 v33, v33, v105
.LBB0_1289:
	s_and_b64 vcc, exec, s[40:41]
	ds_write_b32 v4, v33 offset:10280
	s_cbranch_vccnz .LBB0_1291
	s_ashr_i32 s49, s48, 31
	v_lshl_add_u64 v[6:7], v[2:3], 0, s[48:49]
	v_lshl_add_u64 v[6:7], v[6:7], 2, s[0:1]
	v_mul_f32_e32 v34, v34, v106
.LBB0_1291:
	s_and_b64 vcc, exec, s[40:41]
	ds_write_b32 v4, v34 offset:12336
	s_cbranch_vccnz .LBB0_1293
	s_ashr_i32 s49, s48, 31
	v_lshl_add_u64 v[6:7], v[2:3], 0, s[48:49]
	v_lshl_add_u64 v[6:7], v[6:7], 2, s[0:1]
	v_mul_f32_e32 v31, v31, v107
.LBB0_1293:
	s_and_b64 vcc, exec, s[40:41]
	ds_write_b32 v4, v31 offset:14392
	s_cbranch_vccnz .LBB0_1295
	s_ashr_i32 s49, s48, 31
	v_lshl_add_u64 v[6:7], v[2:3], 0, s[48:49]
	v_lshl_add_u64 v[6:7], v[6:7], 2, s[0:1]
	v_mul_f32_e32 v32, v32, v108
.LBB0_1295:
	s_and_b64 vcc, exec, s[40:41]
	ds_write_b32 v4, v32 offset:16448
	s_cbranch_vccnz .LBB0_1297
	s_ashr_i32 s49, s48, 31
	v_lshl_add_u64 v[6:7], v[2:3], 0, s[48:49]
	v_lshl_add_u64 v[6:7], v[6:7], 2, s[0:1]
	v_mul_f32_e32 v29, v29, v109
.LBB0_1297:
	s_and_b64 vcc, exec, s[40:41]
	ds_write_b32 v4, v29 offset:18504
	s_cbranch_vccnz .LBB0_1299
	s_ashr_i32 s49, s48, 31
	v_lshl_add_u64 v[6:7], v[2:3], 0, s[48:49]
	v_lshl_add_u64 v[6:7], v[6:7], 2, s[0:1]
	v_mul_f32_e32 v30, v30, v110
.LBB0_1299:
	s_and_b64 vcc, exec, s[40:41]
	ds_write_b32 v4, v30 offset:20560
	s_cbranch_vccnz .LBB0_1301
	s_ashr_i32 s49, s48, 31
	v_lshl_add_u64 v[6:7], v[2:3], 0, s[48:49]
	v_lshl_add_u64 v[6:7], v[6:7], 2, s[0:1]
	v_mul_f32_e32 v27, v27, v111
; DI void convert_tile(const CvtJob& jb, int ti, char* lds) {
;     ...
; #pragma unroll
;   for (int i = 0; i < 32; ++i) v[i] = (n < N) ? jb.src[(size_t)(k0 + kr + 2 * i) * N + n] : 0.f;
; #pragma unroll
;   for (int i = 0; i < 32; ++i) { const int k = kr + 2 * i; tile[k * 257 + nn] = jb.kscale ? v[i] * jb.kscale[k0 + k] : v[i]; }
.LBB0_1301:
	s_and_b64 vcc, exec, s[40:41]
	ds_write_b32 v4, v27 offset:22616
	s_cbranch_vccnz .LBB0_1303
	s_ashr_i32 s49, s48, 31
	v_lshl_add_u64 v[6:7], v[2:3], 0, s[48:49]
	v_lshl_add_u64 v[6:7], v[6:7], 2, s[0:1]
	v_mul_f32_e32 v28, v28, v112
.LBB0_1303:
	s_and_b64 vcc, exec, s[40:41]
	ds_write_b32 v4, v28 offset:24672
	s_cbranch_vccnz .LBB0_1305
	s_ashr_i32 s49, s48, 31
	v_lshl_add_u64 v[6:7], v[2:3], 0, s[48:49]
	v_lshl_add_u64 v[6:7], v[6:7], 2, s[0:1]
	v_mul_f32_e32 v25, v25, v113
.LBB0_1305:
	s_and_b64 vcc, exec, s[40:41]
	ds_write_b32 v4, v25 offset:26728
	s_cbranch_vccnz .LBB0_1307
	s_ashr_i32 s49, s48, 31
	v_lshl_add_u64 v[6:7], v[2:3], 0, s[48:49]
	v_lshl_add_u64 v[6:7], v[6:7], 2, s[0:1]
	v_mul_f32_e32 v26, v26, v114
.LBB0_1307:
	s_and_b64 vcc, exec, s[40:41]
	ds_write_b32 v4, v26 offset:28784
	s_cbranch_vccnz .LBB0_1309
	s_ashr_i32 s49, s48, 31
	v_lshl_add_u64 v[6:7], v[2:3], 0, s[48:49]
	v_lshl_add_u64 v[6:7], v[6:7], 2, s[0:1]
	v_mul_f32_e32 v23, v23, v115
.LBB0_1309:
	s_and_b64 vcc, exec, s[40:41]
	ds_write_b32 v4, v23 offset:30840
	s_cbranch_vccnz .LBB0_1311
	s_ashr_i32 s49, s48, 31
	v_lshl_add_u64 v[6:7], v[2:3], 0, s[48:49]
	v_lshl_add_u64 v[6:7], v[6:7], 2, s[0:1]
	v_mul_f32_e32 v24, v24, v116
.LBB0_1311:
	s_and_b64 vcc, exec, s[40:41]
	ds_write_b32 v4, v24 offset:32896
	s_cbranch_vccnz .LBB0_1313
	s_ashr_i32 s49, s48, 31
	v_lshl_add_u64 v[6:7], v[2:3], 0, s[48:49]
	v_lshl_add_u64 v[6:7], v[6:7], 2, s[0:1]
	v_mul_f32_e32 v21, v21, v117
.LBB0_1313:
	s_and_b64 vcc, exec, s[40:41]
	ds_write_b32 v4, v21 offset:34952
	s_cbranch_vccnz .LBB0_1315
	s_ashr_i32 s49, s48, 31
	v_lshl_add_u64 v[6:7], v[2:3], 0, s[48:49]
	v_lshl_add_u64 v[6:7], v[6:7], 2, s[0:1]
	v_mul_f32_e32 v22, v22, v118
.LBB0_1315:
	s_and_b64 vcc, exec, s[40:41]
	ds_write_b32 v4, v22 offset:37008
	s_cbranch_vccnz .LBB0_1317
	s_ashr_i32 s49, s48, 31
	v_lshl_add_u64 v[6:7], v[2:3], 0, s[48:49]
	v_lshl_add_u64 v[6:7], v[6:7], 2, s[0:1]
	v_mul_f32_e32 v19, v19, v119
.LBB0_1317:
	s_and_b64 vcc, exec, s[40:41]
	ds_write_b32 v4, v19 offset:39064
	s_cbranch_vccnz .LBB0_1319
	s_ashr_i32 s49, s48, 31
	v_lshl_add_u64 v[6:7], v[2:3], 0, s[48:49]
	v_lshl_add_u64 v[6:7], v[6:7], 2, s[0:1]
	v_mul_f32_e32 v20, v20, v120
.LBB0_1319:
	s_and_b64 vcc, exec, s[40:41]
	ds_write_b32 v4, v20 offset:41120
	s_cbranch_vccnz .LBB0_1321
	s_ashr_i32 s49, s48, 31
	v_lshl_add_u64 v[6:7], v[2:3], 0, s[48:49]
	v_lshl_add_u64 v[6:7], v[6:7], 2, s[0:1]
	v_mul_f32_e32 v17, v17, v121
.LBB0_1321:
	s_and_b64 vcc, exec, s[40:41]
	ds_write_b32 v4, v17 offset:43176
	s_cbranch_vccnz .LBB0_1323
	s_ashr_i32 s49, s48, 31
	v_lshl_add_u64 v[6:7], v[2:3], 0, s[48:49]
	v_lshl_add_u64 v[6:7], v[6:7], 2, s[0:1]
	v_mul_f32_e32 v18, v18, v122
.LBB0_1323:
	s_and_b64 vcc, exec, s[40:41]
	ds_write_b32 v4, v18 offset:45232
	s_cbranch_vccnz .LBB0_1325
	s_ashr_i32 s49, s48, 31
	v_lshl_add_u64 v[6:7], v[2:3], 0, s[48:49]
	v_lshl_add_u64 v[6:7], v[6:7], 2, s[0:1]
	v_mul_f32_e32 v15, v15, v123
.LBB0_1325:
	s_and_b64 vcc, exec, s[40:41]
	ds_write_b32 v4, v15 offset:47288
	s_cbranch_vccnz .LBB0_1327
	s_ashr_i32 s49, s48, 31
	v_lshl_add_u64 v[6:7], v[2:3], 0, s[48:49]
	v_lshl_add_u64 v[6:7], v[6:7], 2, s[0:1]
	v_mul_f32_e32 v16, v16, v124
.LBB0_1327:
	s_and_b64 vcc, exec, s[40:41]
	ds_write_b32 v4, v16 offset:49344
	s_cbranch_vccnz .LBB0_1329
	s_ashr_i32 s49, s48, 31
	v_lshl_add_u64 v[6:7], v[2:3], 0, s[48:49]
	v_lshl_add_u64 v[6:7], v[6:7], 2, s[0:1]
	v_mul_f32_e32 v13, v13, v125
.LBB0_1329:
	s_and_b64 vcc, exec, s[40:41]
	ds_write_b32 v4, v13 offset:51400
	s_cbranch_vccnz .LBB0_1331
	s_ashr_i32 s49, s48, 31
	v_lshl_add_u64 v[6:7], v[2:3], 0, s[48:49]
	v_lshl_add_u64 v[6:7], v[6:7], 2, s[0:1]
	v_mul_f32_e32 v14, v14, v126
.LBB0_1331:
	s_and_b64 vcc, exec, s[40:41]
	ds_write_b32 v4, v14 offset:53456
	s_cbranch_vccnz .LBB0_1333
	s_ashr_i32 s49, s48, 31
	v_lshl_add_u64 v[6:7], v[2:3], 0, s[48:49]
	v_lshl_add_u64 v[6:7], v[6:7], 2, s[0:1]
	v_mul_f32_e32 v10, v10, v127
.LBB0_1333:
	s_and_b64 vcc, exec, s[40:41]
	ds_write_b32 v4, v10 offset:55512
	s_cbranch_vccnz .LBB0_1335
	s_ashr_i32 s49, s48, 31
	v_lshl_add_u64 v[6:7], v[2:3], 0, s[48:49]
	v_lshl_add_u64 v[6:7], v[6:7], 2, s[0:1]
	v_mul_f32_e32 v12, v12, v128
.LBB0_1335:
	s_and_b64 vcc, exec, s[40:41]
	ds_write_b32 v4, v12 offset:57568
	s_cbranch_vccnz .LBB0_1337
	s_ashr_i32 s49, s48, 31
	v_lshl_add_u64 v[6:7], v[2:3], 0, s[48:49]
	v_lshl_add_u64 v[6:7], v[6:7], 2, s[0:1]
	v_mul_f32_e32 v9, v9, v129
.LBB0_1337:
	s_and_b64 vcc, exec, s[40:41]
	ds_write_b32 v4, v9 offset:59624
	s_cbranch_vccnz .LBB0_1339
	s_ashr_i32 s49, s48, 31
	v_lshl_add_u64 v[6:7], v[2:3], 0, s[48:49]
	v_lshl_add_u64 v[6:7], v[6:7], 2, s[0:1]
	v_mul_f32_e32 v11, v11, v130
.LBB0_1339:
	v_readlane_b32 s4, v253, 50
	v_readlane_b32 s5, v253, 51
	s_and_b64 vcc, exec, s[4:5]
	ds_write_b32 v4, v11 offset:61680
	s_cbranch_vccz .LBB0_1499
	s_ashr_i32 s49, s48, 31
	v_lshl_add_u64 v[2:3], v[2:3], 0, s[48:49]
	v_lshl_add_u64 v[2:3], v[2:3], 2, s[0:1]
	v_mul_f32_e32 v2, v0, v131
	s_cbranch_execnz .LBB0_1342

; DI void convert_tile(const CvtJob& jb, int ti, char* lds) {
;     ...
; #pragma unroll
;   for (int i = 0; i < 32; ++i) v[i] = (n < N) ? jb.src[(size_t)(k0 + kr + 2 * i) * N + n] : 0.f;
; #pragma unroll
;   for (int i = 0; i < 32; ++i) { const int k = kr + 2 * i; tile[k * 257 + nn] = jb.kscale ? v[i] * jb.kscale[k0 + k] : v[i]; }
.LBB0_1426:
	s_or_b64 exec, exec, s[40:41]
	v_readlane_b32 s4, v253, 50
	v_readlane_b32 s5, v253, 51
	s_andn2_b64 vcc, exec, s[4:5]
	s_nop 0
	v_cndmask_b32_e64 v5, 0, 1, s[4:5]
	v_cmp_ne_u32_e64 s[40:41], 1, v5
	s_cbranch_vccnz .LBB0_1428
	v_ashrrev_i32_e32 v5, 31, v4
	v_lshl_add_u64 v[4:5], v[4:5], 2, s[0:1]
	s_waitcnt vmcnt(24)
	global_load_dword v100, v[4:5], off
	global_load_dword v101, v[4:5], off offset:8
	global_load_dword v102, v[4:5], off offset:16
	global_load_dword v103, v[4:5], off offset:24
	global_load_dword v104, v[4:5], off offset:32
	global_load_dword v105, v[4:5], off offset:40
	global_load_dword v106, v[4:5], off offset:48
	global_load_dword v107, v[4:5], off offset:56
	global_load_dword v108, v[4:5], off offset:64
	global_load_dword v109, v[4:5], off offset:72
	global_load_dword v110, v[4:5], off offset:80
	global_load_dword v111, v[4:5], off offset:88
	global_load_dword v112, v[4:5], off offset:96
	global_load_dword v113, v[4:5], off offset:104
	global_load_dword v114, v[4:5], off offset:112
	global_load_dword v115, v[4:5], off offset:120
	global_load_dword v116, v[4:5], off offset:128
	global_load_dword v117, v[4:5], off offset:136
	global_load_dword v118, v[4:5], off offset:144
	global_load_dword v119, v[4:5], off offset:152
	global_load_dword v120, v[4:5], off offset:160
	global_load_dword v121, v[4:5], off offset:168
	global_load_dword v122, v[4:5], off offset:176
	global_load_dword v123, v[4:5], off offset:184
	global_load_dword v124, v[4:5], off offset:192
	global_load_dword v125, v[4:5], off offset:200
	global_load_dword v126, v[4:5], off offset:208
	global_load_dword v127, v[4:5], off offset:216
	global_load_dword v128, v[4:5], off offset:224
	global_load_dword v129, v[4:5], off offset:232
	global_load_dword v130, v[4:5], off offset:240
	global_load_dword v131, v[4:5], off offset:248
	s_waitcnt vmcnt(0)
	v_mul_f32_e32 v3, v3, v100
.LBB0_1428:
	v_and_b32_e32 v4, 0xff, v8
	v_lshl_add_u32 v4, v4, 2, 0
	s_movk_i32 s4, 0x404
	v_mad_i32_i24 v5, v2, s4, v4
	s_waitcnt vmcnt(0)
	ds_write_b32 v5, v3
	s_and_b64 vcc, exec, s[40:41]
	v_ashrrev_i32_e32 v3, 31, v2
	s_cbranch_vccnz .LBB0_1430
	s_ashr_i32 s47, s46, 31
	v_lshl_add_u64 v[6:7], v[2:3], 0, s[46:47]
	v_lshl_add_u64 v[6:7], v[6:7], 2, s[0:1]
	v_mul_f32_e32 v37, v37, v101
.LBB0_1430:
	v_mul_i32_i24_e32 v5, 0x404, v2
	v_add_u32_e32 v4, v5, v4
	s_and_b64 vcc, exec, s[40:41]
	ds_write_b32 v4, v37 offset:2056
	s_cbranch_vccnz .LBB0_1432
	s_ashr_i32 s47, s46, 31
	v_lshl_add_u64 v[6:7], v[2:3], 0, s[46:47]
	v_lshl_add_u64 v[6:7], v[6:7], 2, s[0:1]
	v_mul_f32_e32 v38, v38, v102
.LBB0_1432:
	s_and_b64 vcc, exec, s[40:41]
	ds_write_b32 v4, v38 offset:4112
	s_cbranch_vccnz .LBB0_1434
	s_ashr_i32 s47, s46, 31
	v_lshl_add_u64 v[6:7], v[2:3], 0, s[46:47]
	v_lshl_add_u64 v[6:7], v[6:7], 2, s[0:1]
	v_mul_f32_e32 v35, v35, v103
.LBB0_1434:
	s_and_b64 vcc, exec, s[40:41]
	ds_write_b32 v4, v35 offset:6168
	s_cbranch_vccnz .LBB0_1436
	s_ashr_i32 s47, s46, 31
	v_lshl_add_u64 v[6:7], v[2:3], 0, s[46:47]
	v_lshl_add_u64 v[6:7], v[6:7], 2, s[0:1]
	v_mul_f32_e32 v36, v36, v104
.LBB0_1436:
	s_and_b64 vcc, exec, s[40:41]
	ds_write_b32 v4, v36 offset:8224
	s_cbranch_vccnz .LBB0_1438
	s_ashr_i32 s47, s46, 31
	v_lshl_add_u64 v[6:7], v[2:3], 0, s[46:47]
	v_lshl_add_u64 v[6:7], v[6:7], 2, s[0:1]
	v_mul_f32_e32 v33, v33, v105
.LBB0_1438:
	s_and_b64 vcc, exec, s[40:41]
	ds_write_b32 v4, v33 offset:10280
	s_cbranch_vccnz .LBB0_1440
	s_ashr_i32 s47, s46, 31
	v_lshl_add_u64 v[6:7], v[2:3], 0, s[46:47]
	v_lshl_add_u64 v[6:7], v[6:7], 2, s[0:1]
	v_mul_f32_e32 v34, v34, v106
.LBB0_1440:
	s_and_b64 vcc, exec, s[40:41]
	ds_write_b32 v4, v34 offset:12336
	s_cbranch_vccnz .LBB0_1442
	s_ashr_i32 s47, s46, 31
	v_lshl_add_u64 v[6:7], v[2:3], 0, s[46:47]
	v_lshl_add_u64 v[6:7], v[6:7], 2, s[0:1]
	v_mul_f32_e32 v31, v31, v107
.LBB0_1442:
	s_and_b64 vcc, exec, s[40:41]
	ds_write_b32 v4, v31 offset:14392
	s_cbranch_vccnz .LBB0_1444
	s_ashr_i32 s47, s46, 31
	v_lshl_add_u64 v[6:7], v[2:3], 0, s[46:47]
	v_lshl_add_u64 v[6:7], v[6:7], 2, s[0:1]
	v_mul_f32_e32 v32, v32, v108
.LBB0_1444:
	s_and_b64 vcc, exec, s[40:41]
	ds_write_b32 v4, v32 offset:16448
	s_cbranch_vccnz .LBB0_1446
	s_ashr_i32 s47, s46, 31
	v_lshl_add_u64 v[6:7], v[2:3], 0, s[46:47]
	v_lshl_add_u64 v[6:7], v[6:7], 2, s[0:1]
	v_mul_f32_e32 v29, v29, v109
.LBB0_1446:
	s_and_b64 vcc, exec, s[40:41]
	ds_write_b32 v4, v29 offset:18504
	s_cbranch_vccnz .LBB0_1448
	s_ashr_i32 s47, s46, 31
	v_lshl_add_u64 v[6:7], v[2:3], 0, s[46:47]
	v_lshl_add_u64 v[6:7], v[6:7], 2, s[0:1]
	v_mul_f32_e32 v30, v30, v110
.LBB0_1448:
	s_and_b64 vcc, exec, s[40:41]
	ds_write_b32 v4, v30 offset:20560
	s_cbranch_vccnz .LBB0_1450
	s_ashr_i32 s47, s46, 31
	v_lshl_add_u64 v[6:7], v[2:3], 0, s[46:47]
	v_lshl_add_u64 v[6:7], v[6:7], 2, s[0:1]
	v_mul_f32_e32 v27, v27, v111
; DI void convert_tile(const CvtJob& jb, int ti, char* lds) {
;     ...
; #pragma unroll
;   for (int i = 0; i < 32; ++i) v[i] = (n < N) ? jb.src[(size_t)(k0 + kr + 2 * i) * N + n] : 0.f;
; #pragma unroll
;   for (int i = 0; i < 32; ++i) { const int k = kr + 2 * i; tile[k * 257 + nn] = jb.kscale ? v[i] * jb.kscale[k0 + k] : v[i]; }
.LBB0_1450:
	s_and_b64 vcc, exec, s[40:41]
	ds_write_b32 v4, v27 offset:22616
	s_cbranch_vccnz .LBB0_1452
	s_ashr_i32 s47, s46, 31
	v_lshl_add_u64 v[6:7], v[2:3], 0, s[46:47]
	v_lshl_add_u64 v[6:7], v[6:7], 2, s[0:1]
	v_mul_f32_e32 v28, v28, v112
.LBB0_1452:
	s_and_b64 vcc, exec, s[40:41]
	ds_write_b32 v4, v28 offset:24672
	s_cbranch_vccnz .LBB0_1454
	s_ashr_i32 s47, s46, 31
	v_lshl_add_u64 v[6:7], v[2:3], 0, s[46:47]
	v_lshl_add_u64 v[6:7], v[6:7], 2, s[0:1]
	v_mul_f32_e32 v25, v25, v113
.LBB0_1454:
	s_and_b64 vcc, exec, s[40:41]
	ds_write_b32 v4, v25 offset:26728
	s_cbranch_vccnz .LBB0_1456
	s_ashr_i32 s47, s46, 31
	v_lshl_add_u64 v[6:7], v[2:3], 0, s[46:47]
	v_lshl_add_u64 v[6:7], v[6:7], 2, s[0:1]
	v_mul_f32_e32 v26, v26, v114
.LBB0_1456:
	s_and_b64 vcc, exec, s[40:41]
	ds_write_b32 v4, v26 offset:28784
	s_cbranch_vccnz .LBB0_1458
	s_ashr_i32 s47, s46, 31
	v_lshl_add_u64 v[6:7], v[2:3], 0, s[46:47]
	v_lshl_add_u64 v[6:7], v[6:7], 2, s[0:1]
	v_mul_f32_e32 v23, v23, v115
.LBB0_1458:
	s_and_b64 vcc, exec, s[40:41]
	ds_write_b32 v4, v23 offset:30840
	s_cbranch_vccnz .LBB0_1460
	s_ashr_i32 s47, s46, 31
	v_lshl_add_u64 v[6:7], v[2:3], 0, s[46:47]
	v_lshl_add_u64 v[6:7], v[6:7], 2, s[0:1]
	v_mul_f32_e32 v24, v24, v116
.LBB0_1460:
	s_and_b64 vcc, exec, s[40:41]
	ds_write_b32 v4, v24 offset:32896
	s_cbranch_vccnz .LBB0_1462
	s_ashr_i32 s47, s46, 31
	v_lshl_add_u64 v[6:7], v[2:3], 0, s[46:47]
	v_lshl_add_u64 v[6:7], v[6:7], 2, s[0:1]
	v_mul_f32_e32 v21, v21, v117
.LBB0_1462:
	s_and_b64 vcc, exec, s[40:41]
	ds_write_b32 v4, v21 offset:34952
	s_cbranch_vccnz .LBB0_1464
	s_ashr_i32 s47, s46, 31
	v_lshl_add_u64 v[6:7], v[2:3], 0, s[46:47]
	v_lshl_add_u64 v[6:7], v[6:7], 2, s[0:1]
	v_mul_f32_e32 v22, v22, v118
.LBB0_1464:
	s_and_b64 vcc, exec, s[40:41]
	ds_write_b32 v4, v22 offset:37008
	s_cbranch_vccnz .LBB0_1466
	s_ashr_i32 s47, s46, 31
	v_lshl_add_u64 v[6:7], v[2:3], 0, s[46:47]
	v_lshl_add_u64 v[6:7], v[6:7], 2, s[0:1]
	v_mul_f32_e32 v19, v19, v119
.LBB0_1466:
	s_and_b64 vcc, exec, s[40:41]
	ds_write_b32 v4, v19 offset:39064
	s_cbranch_vccnz .LBB0_1468
	s_ashr_i32 s47, s46, 31
	v_lshl_add_u64 v[6:7], v[2:3], 0, s[46:47]
	v_lshl_add_u64 v[6:7], v[6:7], 2, s[0:1]
	v_mul_f32_e32 v20, v20, v120
.LBB0_1468:
	s_and_b64 vcc, exec, s[40:41]
	ds_write_b32 v4, v20 offset:41120
	s_cbranch_vccnz .LBB0_1470
	s_ashr_i32 s47, s46, 31
	v_lshl_add_u64 v[6:7], v[2:3], 0, s[46:47]
	v_lshl_add_u64 v[6:7], v[6:7], 2, s[0:1]
	v_mul_f32_e32 v17, v17, v121
.LBB0_1470:
	s_and_b64 vcc, exec, s[40:41]
	ds_write_b32 v4, v17 offset:43176
	s_cbranch_vccnz .LBB0_1472
	s_ashr_i32 s47, s46, 31
	v_lshl_add_u64 v[6:7], v[2:3], 0, s[46:47]
	v_lshl_add_u64 v[6:7], v[6:7], 2, s[0:1]
	v_mul_f32_e32 v18, v18, v122
.LBB0_1472:
	s_and_b64 vcc, exec, s[40:41]
	ds_write_b32 v4, v18 offset:45232
	s_cbranch_vccnz .LBB0_1474
	s_ashr_i32 s47, s46, 31
	v_lshl_add_u64 v[6:7], v[2:3], 0, s[46:47]
	v_lshl_add_u64 v[6:7], v[6:7], 2, s[0:1]
	v_mul_f32_e32 v15, v15, v123
.LBB0_1474:
	s_and_b64 vcc, exec, s[40:41]
	ds_write_b32 v4, v15 offset:47288
	s_cbranch_vccnz .LBB0_1476
	s_ashr_i32 s47, s46, 31
	v_lshl_add_u64 v[6:7], v[2:3], 0, s[46:47]
	v_lshl_add_u64 v[6:7], v[6:7], 2, s[0:1]
	v_mul_f32_e32 v16, v16, v124
.LBB0_1476:
	s_and_b64 vcc, exec, s[40:41]
	ds_write_b32 v4, v16 offset:49344
	s_cbranch_vccnz .LBB0_1478
	s_ashr_i32 s47, s46, 31
	v_lshl_add_u64 v[6:7], v[2:3], 0, s[46:47]
	v_lshl_add_u64 v[6:7], v[6:7], 2, s[0:1]
	v_mul_f32_e32 v13, v13, v125
.LBB0_1478:
	s_and_b64 vcc, exec, s[40:41]
	ds_write_b32 v4, v13 offset:51400
	s_cbranch_vccnz .LBB0_1480
	s_ashr_i32 s47, s46, 31
	v_lshl_add_u64 v[6:7], v[2:3], 0, s[46:47]
	v_lshl_add_u64 v[6:7], v[6:7], 2, s[0:1]
	v_mul_f32_e32 v14, v14, v126
.LBB0_1480:
	s_and_b64 vcc, exec, s[40:41]
	ds_write_b32 v4, v14 offset:53456
	s_cbranch_vccnz .LBB0_1482
	s_ashr_i32 s47, s46, 31
	v_lshl_add_u64 v[6:7], v[2:3], 0, s[46:47]
	v_lshl_add_u64 v[6:7], v[6:7], 2, s[0:1]
	v_mul_f32_e32 v10, v10, v127
.LBB0_1482:
	s_and_b64 vcc, exec, s[40:41]
	ds_write_b32 v4, v10 offset:55512
	s_cbranch_vccnz .LBB0_1484
	s_ashr_i32 s47, s46, 31
	v_lshl_add_u64 v[6:7], v[2:3], 0, s[46:47]
	v_lshl_add_u64 v[6:7], v[6:7], 2, s[0:1]
	v_mul_f32_e32 v12, v12, v128
.LBB0_1484:
	s_and_b64 vcc, exec, s[40:41]
	ds_write_b32 v4, v12 offset:57568
	s_cbranch_vccnz .LBB0_1486
	s_ashr_i32 s47, s46, 31
	v_lshl_add_u64 v[6:7], v[2:3], 0, s[46:47]
	v_lshl_add_u64 v[6:7], v[6:7], 2, s[0:1]
	v_mul_f32_e32 v9, v9, v129
.LBB0_1486:
	s_and_b64 vcc, exec, s[40:41]
	ds_write_b32 v4, v9 offset:59624
	s_cbranch_vccnz .LBB0_1488
	s_ashr_i32 s47, s46, 31
	v_lshl_add_u64 v[6:7], v[2:3], 0, s[46:47]
	v_lshl_add_u64 v[6:7], v[6:7], 2, s[0:1]
	v_mul_f32_e32 v11, v11, v130
.LBB0_1488:
	v_readlane_b32 s4, v253, 50
	v_readlane_b32 s5, v253, 51
	s_and_b64 vcc, exec, s[4:5]
	ds_write_b32 v4, v11 offset:61680
	s_cbranch_vccz .LBB0_1500
	s_ashr_i32 s47, s46, 31
	v_lshl_add_u64 v[2:3], v[2:3], 0, s[46:47]
	v_lshl_add_u64 v[2:3], v[2:3], 2, s[0:1]
	v_mul_f32_e32 v2, v0, v131
	s_cbranch_execnz .LBB0_1491

; DI void convert_tile(const CvtJob& jb, int ti, char* lds) {
;     ...
; #pragma unroll
;   for (int i = 0; i < 32; ++i) v[i] = (n < N) ? jb.src[(size_t)(k0 + kr + 2 * i) * N + n] : 0.f;
; #pragma unroll
;   for (int i = 0; i < 32; ++i) { const int k = kr + 2 * i; tile[k * 257 + nn] = jb.kscale ? v[i] * jb.kscale[k0 + k] : v[i]; }
.LBB0_1576:
	s_or_b64 exec, exec, s[40:41]
	v_readlane_b32 s4, v252, 33
	v_readlane_b32 s5, v252, 34
	s_andn2_b64 vcc, exec, s[4:5]
	s_nop 0
	v_cndmask_b32_e64 v5, 0, 1, s[4:5]
	v_cmp_ne_u32_e64 s[40:41], 1, v5
	s_cbranch_vccnz .LBB0_1578
	v_readlane_b32 s44, v253, 56
	v_ashrrev_i32_e32 v5, 31, v4
	v_readlane_b32 s46, v253, 58
	v_readlane_b32 s47, v253, 59
	v_readlane_b32 s45, v253, 57
	v_readlane_b32 s48, v253, 60
	v_lshl_add_u64 v[4:5], v[4:5], 2, s[46:47]
	s_waitcnt vmcnt(24)
	global_load_dword v100, v[4:5], off
	global_load_dword v101, v[4:5], off offset:8
	global_load_dword v102, v[4:5], off offset:16
	global_load_dword v103, v[4:5], off offset:24
	global_load_dword v104, v[4:5], off offset:32
	global_load_dword v105, v[4:5], off offset:40
	global_load_dword v106, v[4:5], off offset:48
	global_load_dword v107, v[4:5], off offset:56
	global_load_dword v108, v[4:5], off offset:64
	global_load_dword v109, v[4:5], off offset:72
	global_load_dword v110, v[4:5], off offset:80
	global_load_dword v111, v[4:5], off offset:88
	global_load_dword v112, v[4:5], off offset:96
	global_load_dword v113, v[4:5], off offset:104
	global_load_dword v114, v[4:5], off offset:112
	global_load_dword v115, v[4:5], off offset:120
	global_load_dword v116, v[4:5], off offset:128
	global_load_dword v117, v[4:5], off offset:136
	global_load_dword v118, v[4:5], off offset:144
	global_load_dword v119, v[4:5], off offset:152
	global_load_dword v120, v[4:5], off offset:160
	global_load_dword v121, v[4:5], off offset:168
	global_load_dword v122, v[4:5], off offset:176
	global_load_dword v123, v[4:5], off offset:184
	global_load_dword v124, v[4:5], off offset:192
	global_load_dword v125, v[4:5], off offset:200
	global_load_dword v126, v[4:5], off offset:208
	global_load_dword v127, v[4:5], off offset:216
	global_load_dword v128, v[4:5], off offset:224
	global_load_dword v129, v[4:5], off offset:232
	global_load_dword v130, v[4:5], off offset:240
	global_load_dword v131, v[4:5], off offset:248
	v_readlane_b32 s49, v253, 61
	v_readlane_b32 s50, v253, 62
	v_readlane_b32 s51, v253, 63
	v_readlane_b32 s52, v254, 0
	v_readlane_b32 s53, v254, 1
	v_readlane_b32 s54, v254, 2
	v_readlane_b32 s55, v254, 3
	v_readlane_b32 s56, v254, 4
	v_readlane_b32 s57, v254, 5
	v_readlane_b32 s58, v254, 6
	v_readlane_b32 s59, v254, 7
	s_waitcnt vmcnt(0)
	v_mul_f32_e32 v3, v3, v100
.LBB0_1578:
	v_and_b32_e32 v4, 0xff, v8
	v_lshl_add_u32 v4, v4, 2, 0
	s_movk_i32 s4, 0x404
	v_mad_i32_i24 v5, v2, s4, v4
	s_waitcnt vmcnt(0)
	ds_write_b32 v5, v3
	s_and_b64 vcc, exec, s[40:41]
	v_ashrrev_i32_e32 v3, 31, v2
	s_cbranch_vccnz .LBB0_1580
	s_ashr_i32 s31, s30, 31
	v_readlane_b32 s4, v253, 56
	v_lshl_add_u64 v[6:7], v[2:3], 0, s[30:31]
	v_readlane_b32 s6, v253, 58
	v_readlane_b32 s7, v253, 59
	v_readlane_b32 s5, v253, 57
	v_readlane_b32 s8, v253, 60
	v_lshl_add_u64 v[6:7], v[6:7], 2, s[6:7]
	v_readlane_b32 s9, v253, 61
	v_readlane_b32 s10, v253, 62
	v_readlane_b32 s11, v253, 63
	v_readlane_b32 s12, v254, 0
	v_readlane_b32 s13, v254, 1
	v_readlane_b32 s14, v254, 2
	v_readlane_b32 s15, v254, 3
	v_readlane_b32 s16, v254, 4
	v_readlane_b32 s17, v254, 5
	v_readlane_b32 s18, v254, 6
	v_readlane_b32 s19, v254, 7
	v_mul_f32_e32 v38, v38, v101
.LBB0_1580:
	v_mul_i32_i24_e32 v5, 0x404, v2
	v_add_u32_e32 v4, v5, v4
	s_and_b64 vcc, exec, s[40:41]
	ds_write_b32 v4, v38 offset:2056
	s_cbranch_vccnz .LBB0_1582
	s_ashr_i32 s31, s30, 31
	v_readlane_b32 s4, v253, 56
	v_lshl_add_u64 v[6:7], v[2:3], 0, s[30:31]
	v_readlane_b32 s6, v253, 58
	v_readlane_b32 s7, v253, 59
	v_readlane_b32 s5, v253, 57
	v_readlane_b32 s8, v253, 60
	v_lshl_add_u64 v[6:7], v[6:7], 2, s[6:7]
	v_readlane_b32 s9, v253, 61
	v_readlane_b32 s10, v253, 62
	v_readlane_b32 s11, v253, 63
	v_readlane_b32 s12, v254, 0
	v_readlane_b32 s13, v254, 1
	v_readlane_b32 s14, v254, 2
	v_readlane_b32 s15, v254, 3
	v_readlane_b32 s16, v254, 4
	v_readlane_b32 s17, v254, 5
	v_readlane_b32 s18, v254, 6
	v_readlane_b32 s19, v254, 7
	v_mul_f32_e32 v37, v37, v102
.LBB0_1582:
	s_and_b64 vcc, exec, s[40:41]
	ds_write_b32 v4, v37 offset:4112
	s_cbranch_vccnz .LBB0_1584
	s_ashr_i32 s31, s30, 31
	v_readlane_b32 s4, v253, 56
	v_lshl_add_u64 v[6:7], v[2:3], 0, s[30:31]
	v_readlane_b32 s6, v253, 58
	v_readlane_b32 s7, v253, 59
	v_readlane_b32 s5, v253, 57
	v_readlane_b32 s8, v253, 60
	v_lshl_add_u64 v[6:7], v[6:7], 2, s[6:7]
	v_readlane_b32 s9, v253, 61
	v_readlane_b32 s10, v253, 62
	v_readlane_b32 s11, v253, 63
	v_readlane_b32 s12, v254, 0
	v_readlane_b32 s13, v254, 1
	v_readlane_b32 s14, v254, 2
	v_readlane_b32 s15, v254, 3
	v_readlane_b32 s16, v254, 4
	v_readlane_b32 s17, v254, 5
	v_readlane_b32 s18, v254, 6
	v_readlane_b32 s19, v254, 7
	v_mul_f32_e32 v36, v36, v103
.LBB0_1584:
	s_and_b64 vcc, exec, s[40:41]
	ds_write_b32 v4, v36 offset:6168
	s_cbranch_vccnz .LBB0_1586
	s_ashr_i32 s31, s30, 31
	v_readlane_b32 s4, v253, 56
	v_lshl_add_u64 v[6:7], v[2:3], 0, s[30:31]
	v_readlane_b32 s6, v253, 58
	v_readlane_b32 s7, v253, 59
	v_readlane_b32 s5, v253, 57
	v_readlane_b32 s8, v253, 60
	v_lshl_add_u64 v[6:7], v[6:7], 2, s[6:7]
	v_readlane_b32 s9, v253, 61
	v_readlane_b32 s10, v253, 62
	v_readlane_b32 s11, v253, 63
	v_readlane_b32 s12, v254, 0
	v_readlane_b32 s13, v254, 1
	v_readlane_b32 s14, v254, 2
	v_readlane_b32 s15, v254, 3
	v_readlane_b32 s16, v254, 4
	v_readlane_b32 s17, v254, 5
	v_readlane_b32 s18, v254, 6
	v_readlane_b32 s19, v254, 7
	v_mul_f32_e32 v35, v35, v104
; DI void convert_tile(const CvtJob& jb, int ti, char* lds) {
;     ...
; #pragma unroll
;   for (int i = 0; i < 32; ++i) v[i] = (n < N) ? jb.src[(size_t)(k0 + kr + 2 * i) * N + n] : 0.f;
; #pragma unroll
;   for (int i = 0; i < 32; ++i) { const int k = kr + 2 * i; tile[k * 257 + nn] = jb.kscale ? v[i] * jb.kscale[k0 + k] : v[i]; }
.LBB0_1586:
	s_and_b64 vcc, exec, s[40:41]
	ds_write_b32 v4, v35 offset:8224
	s_cbranch_vccnz .LBB0_1588
	s_ashr_i32 s31, s30, 31
	v_readlane_b32 s4, v253, 56
	v_lshl_add_u64 v[6:7], v[2:3], 0, s[30:31]
	v_readlane_b32 s6, v253, 58
	v_readlane_b32 s7, v253, 59
	v_readlane_b32 s5, v253, 57
	v_readlane_b32 s8, v253, 60
	v_lshl_add_u64 v[6:7], v[6:7], 2, s[6:7]
	v_readlane_b32 s9, v253, 61
	v_readlane_b32 s10, v253, 62
	v_readlane_b32 s11, v253, 63
	v_readlane_b32 s12, v254, 0
	v_readlane_b32 s13, v254, 1
	v_readlane_b32 s14, v254, 2
	v_readlane_b32 s15, v254, 3
	v_readlane_b32 s16, v254, 4
	v_readlane_b32 s17, v254, 5
	v_readlane_b32 s18, v254, 6
	v_readlane_b32 s19, v254, 7
	v_mul_f32_e32 v34, v34, v105
.LBB0_1588:
	s_and_b64 vcc, exec, s[40:41]
	ds_write_b32 v4, v34 offset:10280
	s_cbranch_vccnz .LBB0_1590
	s_ashr_i32 s31, s30, 31
	v_readlane_b32 s4, v253, 56
	v_lshl_add_u64 v[6:7], v[2:3], 0, s[30:31]
	v_readlane_b32 s6, v253, 58
	v_readlane_b32 s7, v253, 59
	v_readlane_b32 s5, v253, 57
	v_readlane_b32 s8, v253, 60
	v_lshl_add_u64 v[6:7], v[6:7], 2, s[6:7]
	v_readlane_b32 s9, v253, 61
	v_readlane_b32 s10, v253, 62
	v_readlane_b32 s11, v253, 63
	v_readlane_b32 s12, v254, 0
	v_readlane_b32 s13, v254, 1
	v_readlane_b32 s14, v254, 2
	v_readlane_b32 s15, v254, 3
	v_readlane_b32 s16, v254, 4
	v_readlane_b32 s17, v254, 5
	v_readlane_b32 s18, v254, 6
	v_readlane_b32 s19, v254, 7
	v_mul_f32_e32 v33, v33, v106
.LBB0_1590:
	s_and_b64 vcc, exec, s[40:41]
	ds_write_b32 v4, v33 offset:12336
	s_cbranch_vccnz .LBB0_1592
	s_ashr_i32 s31, s30, 31
	v_readlane_b32 s4, v253, 56
	v_lshl_add_u64 v[6:7], v[2:3], 0, s[30:31]
	v_readlane_b32 s6, v253, 58
	v_readlane_b32 s7, v253, 59
	v_readlane_b32 s5, v253, 57
	v_readlane_b32 s8, v253, 60
	v_lshl_add_u64 v[6:7], v[6:7], 2, s[6:7]
	v_readlane_b32 s9, v253, 61
	v_readlane_b32 s10, v253, 62
	v_readlane_b32 s11, v253, 63
	v_readlane_b32 s12, v254, 0
	v_readlane_b32 s13, v254, 1
	v_readlane_b32 s14, v254, 2
	v_readlane_b32 s15, v254, 3
	v_readlane_b32 s16, v254, 4
	v_readlane_b32 s17, v254, 5
	v_readlane_b32 s18, v254, 6
	v_readlane_b32 s19, v254, 7
	v_mul_f32_e32 v32, v32, v107
.LBB0_1592:
	s_and_b64 vcc, exec, s[40:41]
	ds_write_b32 v4, v32 offset:14392
	s_cbranch_vccnz .LBB0_1594
	s_ashr_i32 s31, s30, 31
	v_readlane_b32 s4, v253, 56
	v_lshl_add_u64 v[6:7], v[2:3], 0, s[30:31]
	v_readlane_b32 s6, v253, 58
	v_readlane_b32 s7, v253, 59
	v_readlane_b32 s5, v253, 57
	v_readlane_b32 s8, v253, 60
	v_lshl_add_u64 v[6:7], v[6:7], 2, s[6:7]
	v_readlane_b32 s9, v253, 61
	v_readlane_b32 s10, v253, 62
	v_readlane_b32 s11, v253, 63
	v_readlane_b32 s12, v254, 0
	v_readlane_b32 s13, v254, 1
	v_readlane_b32 s14, v254, 2
	v_readlane_b32 s15, v254, 3
	v_readlane_b32 s16, v254, 4
	v_readlane_b32 s17, v254, 5
	v_readlane_b32 s18, v254, 6
	v_readlane_b32 s19, v254, 7
	v_mul_f32_e32 v31, v31, v108
.LBB0_1594:
	s_and_b64 vcc, exec, s[40:41]
	ds_write_b32 v4, v31 offset:16448
	s_cbranch_vccnz .LBB0_1596
	s_ashr_i32 s31, s30, 31
	v_readlane_b32 s4, v253, 56
	v_lshl_add_u64 v[6:7], v[2:3], 0, s[30:31]
	v_readlane_b32 s6, v253, 58
	v_readlane_b32 s7, v253, 59
	v_readlane_b32 s5, v253, 57
	v_readlane_b32 s8, v253, 60
	v_lshl_add_u64 v[6:7], v[6:7], 2, s[6:7]
	v_readlane_b32 s9, v253, 61
	v_readlane_b32 s10, v253, 62
	v_readlane_b32 s11, v253, 63
	v_readlane_b32 s12, v254, 0
	v_readlane_b32 s13, v254, 1
	v_readlane_b32 s14, v254, 2
	v_readlane_b32 s15, v254, 3
	v_readlane_b32 s16, v254, 4
	v_readlane_b32 s17, v254, 5
	v_readlane_b32 s18, v254, 6
	v_readlane_b32 s19, v254, 7
	v_mul_f32_e32 v30, v30, v109
.LBB0_1596:
	s_and_b64 vcc, exec, s[40:41]
	ds_write_b32 v4, v30 offset:18504
	s_cbranch_vccnz .LBB0_1598
	s_ashr_i32 s31, s30, 31
	v_readlane_b32 s4, v253, 56
	v_lshl_add_u64 v[6:7], v[2:3], 0, s[30:31]
	v_readlane_b32 s6, v253, 58
	v_readlane_b32 s7, v253, 59
	v_readlane_b32 s5, v253, 57
	v_readlane_b32 s8, v253, 60
	v_lshl_add_u64 v[6:7], v[6:7], 2, s[6:7]
	v_readlane_b32 s9, v253, 61
	v_readlane_b32 s10, v253, 62
	v_readlane_b32 s11, v253, 63
	v_readlane_b32 s12, v254, 0
	v_readlane_b32 s13, v254, 1
	v_readlane_b32 s14, v254, 2
	v_readlane_b32 s15, v254, 3
	v_readlane_b32 s16, v254, 4
	v_readlane_b32 s17, v254, 5
	v_readlane_b32 s18, v254, 6
	v_readlane_b32 s19, v254, 7
	v_mul_f32_e32 v29, v29, v110
.LBB0_1598:
	s_and_b64 vcc, exec, s[40:41]
	ds_write_b32 v4, v29 offset:20560
	s_cbranch_vccnz .LBB0_1600
	s_ashr_i32 s31, s30, 31
	v_readlane_b32 s4, v253, 56
	v_lshl_add_u64 v[6:7], v[2:3], 0, s[30:31]
	v_readlane_b32 s6, v253, 58
	v_readlane_b32 s7, v253, 59
	v_readlane_b32 s5, v253, 57
	v_readlane_b32 s8, v253, 60
	v_lshl_add_u64 v[6:7], v[6:7], 2, s[6:7]
	v_readlane_b32 s9, v253, 61
	v_readlane_b32 s10, v253, 62
	v_readlane_b32 s11, v253, 63
	v_readlane_b32 s12, v254, 0
	v_readlane_b32 s13, v254, 1
	v_readlane_b32 s14, v254, 2
	v_readlane_b32 s15, v254, 3
	v_readlane_b32 s16, v254, 4
	v_readlane_b32 s17, v254, 5
	v_readlane_b32 s18, v254, 6
	v_readlane_b32 s19, v254, 7
	v_mul_f32_e32 v28, v28, v111
.LBB0_1600:
	s_and_b64 vcc, exec, s[40:41]
	ds_write_b32 v4, v28 offset:22616
	s_cbranch_vccnz .LBB0_1602
	s_ashr_i32 s31, s30, 31
	v_readlane_b32 s4, v253, 56
	v_lshl_add_u64 v[6:7], v[2:3], 0, s[30:31]
	v_readlane_b32 s6, v253, 58
	v_readlane_b32 s7, v253, 59
	v_readlane_b32 s5, v253, 57
	v_readlane_b32 s8, v253, 60
	v_lshl_add_u64 v[6:7], v[6:7], 2, s[6:7]
	v_readlane_b32 s9, v253, 61
	v_readlane_b32 s10, v253, 62
	v_readlane_b32 s11, v253, 63
	v_readlane_b32 s12, v254, 0
	v_readlane_b32 s13, v254, 1
	v_readlane_b32 s14, v254, 2
	v_readlane_b32 s15, v254, 3
	v_readlane_b32 s16, v254, 4
	v_readlane_b32 s17, v254, 5
	v_readlane_b32 s18, v254, 6
	v_readlane_b32 s19, v254, 7
	v_mul_f32_e32 v27, v27, v112
; DI void convert_tile(const CvtJob& jb, int ti, char* lds) {
;     ...
; #pragma unroll
;   for (int i = 0; i < 32; ++i) v[i] = (n < N) ? jb.src[(size_t)(k0 + kr + 2 * i) * N + n] : 0.f;
; #pragma unroll
;   for (int i = 0; i < 32; ++i) { const int k = kr + 2 * i; tile[k * 257 + nn] = jb.kscale ? v[i] * jb.kscale[k0 + k] : v[i]; }
.LBB0_1602:
	s_and_b64 vcc, exec, s[40:41]
	ds_write_b32 v4, v27 offset:24672
	s_cbranch_vccnz .LBB0_1604
	s_ashr_i32 s31, s30, 31
	v_readlane_b32 s4, v253, 56
	v_lshl_add_u64 v[6:7], v[2:3], 0, s[30:31]
	v_readlane_b32 s6, v253, 58
	v_readlane_b32 s7, v253, 59
	v_readlane_b32 s5, v253, 57
	v_readlane_b32 s8, v253, 60
	v_lshl_add_u64 v[6:7], v[6:7], 2, s[6:7]
	v_readlane_b32 s9, v253, 61
	v_readlane_b32 s10, v253, 62
	v_readlane_b32 s11, v253, 63
	v_readlane_b32 s12, v254, 0
	v_readlane_b32 s13, v254, 1
	v_readlane_b32 s14, v254, 2
	v_readlane_b32 s15, v254, 3
	v_readlane_b32 s16, v254, 4
	v_readlane_b32 s17, v254, 5
	v_readlane_b32 s18, v254, 6
	v_readlane_b32 s19, v254, 7
	v_mul_f32_e32 v26, v26, v113
.LBB0_1604:
	s_and_b64 vcc, exec, s[40:41]
	ds_write_b32 v4, v26 offset:26728
	s_cbranch_vccnz .LBB0_1606
	s_ashr_i32 s31, s30, 31
	v_readlane_b32 s4, v253, 56
	v_lshl_add_u64 v[6:7], v[2:3], 0, s[30:31]
	v_readlane_b32 s6, v253, 58
	v_readlane_b32 s7, v253, 59
	v_readlane_b32 s5, v253, 57
	v_readlane_b32 s8, v253, 60
	v_lshl_add_u64 v[6:7], v[6:7], 2, s[6:7]
	v_readlane_b32 s9, v253, 61
	v_readlane_b32 s10, v253, 62
	v_readlane_b32 s11, v253, 63
	v_readlane_b32 s12, v254, 0
	v_readlane_b32 s13, v254, 1
	v_readlane_b32 s14, v254, 2
	v_readlane_b32 s15, v254, 3
	v_readlane_b32 s16, v254, 4
	v_readlane_b32 s17, v254, 5
	v_readlane_b32 s18, v254, 6
	v_readlane_b32 s19, v254, 7
	v_mul_f32_e32 v25, v25, v114
.LBB0_1606:
	s_and_b64 vcc, exec, s[40:41]
	ds_write_b32 v4, v25 offset:28784
	s_cbranch_vccnz .LBB0_1608
	s_ashr_i32 s31, s30, 31
	v_readlane_b32 s4, v253, 56
	v_lshl_add_u64 v[6:7], v[2:3], 0, s[30:31]
	v_readlane_b32 s6, v253, 58
	v_readlane_b32 s7, v253, 59
	v_readlane_b32 s5, v253, 57
	v_readlane_b32 s8, v253, 60
	v_lshl_add_u64 v[6:7], v[6:7], 2, s[6:7]
	v_readlane_b32 s9, v253, 61
	v_readlane_b32 s10, v253, 62
	v_readlane_b32 s11, v253, 63
	v_readlane_b32 s12, v254, 0
	v_readlane_b32 s13, v254, 1
	v_readlane_b32 s14, v254, 2
	v_readlane_b32 s15, v254, 3
	v_readlane_b32 s16, v254, 4
	v_readlane_b32 s17, v254, 5
	v_readlane_b32 s18, v254, 6
	v_readlane_b32 s19, v254, 7
	v_mul_f32_e32 v24, v24, v115
.LBB0_1608:
	s_and_b64 vcc, exec, s[40:41]
	ds_write_b32 v4, v24 offset:30840
	s_cbranch_vccnz .LBB0_1610
	s_ashr_i32 s31, s30, 31
	v_readlane_b32 s4, v253, 56
	v_lshl_add_u64 v[6:7], v[2:3], 0, s[30:31]
	v_readlane_b32 s6, v253, 58
	v_readlane_b32 s7, v253, 59
	v_readlane_b32 s5, v253, 57
	v_readlane_b32 s8, v253, 60
	v_lshl_add_u64 v[6:7], v[6:7], 2, s[6:7]
	v_readlane_b32 s9, v253, 61
	v_readlane_b32 s10, v253, 62
	v_readlane_b32 s11, v253, 63
	v_readlane_b32 s12, v254, 0
	v_readlane_b32 s13, v254, 1
	v_readlane_b32 s14, v254, 2
	v_readlane_b32 s15, v254, 3
	v_readlane_b32 s16, v254, 4
	v_readlane_b32 s17, v254, 5
	v_readlane_b32 s18, v254, 6
	v_readlane_b32 s19, v254, 7
	v_mul_f32_e32 v23, v23, v116
.LBB0_1610:
	s_and_b64 vcc, exec, s[40:41]
	ds_write_b32 v4, v23 offset:32896
	s_cbranch_vccnz .LBB0_1612
	s_ashr_i32 s31, s30, 31
	v_readlane_b32 s4, v253, 56
	v_lshl_add_u64 v[6:7], v[2:3], 0, s[30:31]
	v_readlane_b32 s6, v253, 58
	v_readlane_b32 s7, v253, 59
	v_readlane_b32 s5, v253, 57
	v_readlane_b32 s8, v253, 60
	v_lshl_add_u64 v[6:7], v[6:7], 2, s[6:7]
	v_readlane_b32 s9, v253, 61
	v_readlane_b32 s10, v253, 62
	v_readlane_b32 s11, v253, 63
	v_readlane_b32 s12, v254, 0
	v_readlane_b32 s13, v254, 1
	v_readlane_b32 s14, v254, 2
	v_readlane_b32 s15, v254, 3
	v_readlane_b32 s16, v254, 4
	v_readlane_b32 s17, v254, 5
	v_readlane_b32 s18, v254, 6
	v_readlane_b32 s19, v254, 7
	v_mul_f32_e32 v22, v22, v117
.LBB0_1612:
	s_and_b64 vcc, exec, s[40:41]
	ds_write_b32 v4, v22 offset:34952
	s_cbranch_vccnz .LBB0_1614
	s_ashr_i32 s31, s30, 31
	v_readlane_b32 s4, v253, 56
	v_lshl_add_u64 v[6:7], v[2:3], 0, s[30:31]
	v_readlane_b32 s6, v253, 58
	v_readlane_b32 s7, v253, 59
	v_readlane_b32 s5, v253, 57
	v_readlane_b32 s8, v253, 60
	v_lshl_add_u64 v[6:7], v[6:7], 2, s[6:7]
	v_readlane_b32 s9, v253, 61
	v_readlane_b32 s10, v253, 62
	v_readlane_b32 s11, v253, 63
	v_readlane_b32 s12, v254, 0
	v_readlane_b32 s13, v254, 1
	v_readlane_b32 s14, v254, 2
	v_readlane_b32 s15, v254, 3
	v_readlane_b32 s16, v254, 4
	v_readlane_b32 s17, v254, 5
	v_readlane_b32 s18, v254, 6
	v_readlane_b32 s19, v254, 7
	v_mul_f32_e32 v21, v21, v118
.LBB0_1614:
	s_and_b64 vcc, exec, s[40:41]
	ds_write_b32 v4, v21 offset:37008
	s_cbranch_vccnz .LBB0_1616
	s_ashr_i32 s31, s30, 31
	v_readlane_b32 s4, v253, 56
	v_lshl_add_u64 v[6:7], v[2:3], 0, s[30:31]
	v_readlane_b32 s6, v253, 58
	v_readlane_b32 s7, v253, 59
	v_readlane_b32 s5, v253, 57
	v_readlane_b32 s8, v253, 60
	v_lshl_add_u64 v[6:7], v[6:7], 2, s[6:7]
	v_readlane_b32 s9, v253, 61
	v_readlane_b32 s10, v253, 62
	v_readlane_b32 s11, v253, 63
	v_readlane_b32 s12, v254, 0
	v_readlane_b32 s13, v254, 1
	v_readlane_b32 s14, v254, 2
	v_readlane_b32 s15, v254, 3
	v_readlane_b32 s16, v254, 4
	v_readlane_b32 s17, v254, 5
	v_readlane_b32 s18, v254, 6
	v_readlane_b32 s19, v254, 7
	v_mul_f32_e32 v20, v20, v119
.LBB0_1616:
	s_and_b64 vcc, exec, s[40:41]
	ds_write_b32 v4, v20 offset:39064
	s_cbranch_vccnz .LBB0_1618
	s_ashr_i32 s31, s30, 31
	v_readlane_b32 s4, v253, 56
	v_lshl_add_u64 v[6:7], v[2:3], 0, s[30:31]
	v_readlane_b32 s6, v253, 58
	v_readlane_b32 s7, v253, 59
	v_readlane_b32 s5, v253, 57
	v_readlane_b32 s8, v253, 60
	v_lshl_add_u64 v[6:7], v[6:7], 2, s[6:7]
	v_readlane_b32 s9, v253, 61
	v_readlane_b32 s10, v253, 62
	v_readlane_b32 s11, v253, 63
	v_readlane_b32 s12, v254, 0
	v_readlane_b32 s13, v254, 1
	v_readlane_b32 s14, v254, 2
	v_readlane_b32 s15, v254, 3
	v_readlane_b32 s16, v254, 4
	v_readlane_b32 s17, v254, 5
	v_readlane_b32 s18, v254, 6
	v_readlane_b32 s19, v254, 7
	v_mul_f32_e32 v19, v19, v120
; DI void convert_tile(const CvtJob& jb, int ti, char* lds) {
;     ...
; #pragma unroll
;   for (int i = 0; i < 32; ++i) v[i] = (n < N) ? jb.src[(size_t)(k0 + kr + 2 * i) * N + n] : 0.f;
; #pragma unroll
;   for (int i = 0; i < 32; ++i) { const int k = kr + 2 * i; tile[k * 257 + nn] = jb.kscale ? v[i] * jb.kscale[k0 + k] : v[i]; }
.LBB0_1618:
	s_and_b64 vcc, exec, s[40:41]
	ds_write_b32 v4, v19 offset:41120
	s_cbranch_vccnz .LBB0_1620
	s_ashr_i32 s31, s30, 31
	v_readlane_b32 s4, v253, 56
	v_lshl_add_u64 v[6:7], v[2:3], 0, s[30:31]
	v_readlane_b32 s6, v253, 58
	v_readlane_b32 s7, v253, 59
	v_readlane_b32 s5, v253, 57
	v_readlane_b32 s8, v253, 60
	v_lshl_add_u64 v[6:7], v[6:7], 2, s[6:7]
	v_readlane_b32 s9, v253, 61
	v_readlane_b32 s10, v253, 62
	v_readlane_b32 s11, v253, 63
	v_readlane_b32 s12, v254, 0
	v_readlane_b32 s13, v254, 1
	v_readlane_b32 s14, v254, 2
	v_readlane_b32 s15, v254, 3
	v_readlane_b32 s16, v254, 4
	v_readlane_b32 s17, v254, 5
	v_readlane_b32 s18, v254, 6
	v_readlane_b32 s19, v254, 7
	v_mul_f32_e32 v18, v18, v121
.LBB0_1620:
	s_and_b64 vcc, exec, s[40:41]
	ds_write_b32 v4, v18 offset:43176
	s_cbranch_vccnz .LBB0_1622
	s_ashr_i32 s31, s30, 31
	v_readlane_b32 s4, v253, 56
	v_lshl_add_u64 v[6:7], v[2:3], 0, s[30:31]
	v_readlane_b32 s6, v253, 58
	v_readlane_b32 s7, v253, 59
	v_readlane_b32 s5, v253, 57
	v_readlane_b32 s8, v253, 60
	v_lshl_add_u64 v[6:7], v[6:7], 2, s[6:7]
	v_readlane_b32 s9, v253, 61
	v_readlane_b32 s10, v253, 62
	v_readlane_b32 s11, v253, 63
	v_readlane_b32 s12, v254, 0
	v_readlane_b32 s13, v254, 1
	v_readlane_b32 s14, v254, 2
	v_readlane_b32 s15, v254, 3
	v_readlane_b32 s16, v254, 4
	v_readlane_b32 s17, v254, 5
	v_readlane_b32 s18, v254, 6
	v_readlane_b32 s19, v254, 7
	v_mul_f32_e32 v17, v17, v122
.LBB0_1622:
	s_and_b64 vcc, exec, s[40:41]
	ds_write_b32 v4, v17 offset:45232
	s_cbranch_vccnz .LBB0_1624
	s_ashr_i32 s31, s30, 31
	v_readlane_b32 s4, v253, 56
	v_lshl_add_u64 v[6:7], v[2:3], 0, s[30:31]
	v_readlane_b32 s6, v253, 58
	v_readlane_b32 s7, v253, 59
	v_readlane_b32 s5, v253, 57
	v_readlane_b32 s8, v253, 60
	v_lshl_add_u64 v[6:7], v[6:7], 2, s[6:7]
	v_readlane_b32 s9, v253, 61
	v_readlane_b32 s10, v253, 62
	v_readlane_b32 s11, v253, 63
	v_readlane_b32 s12, v254, 0
	v_readlane_b32 s13, v254, 1
	v_readlane_b32 s14, v254, 2
	v_readlane_b32 s15, v254, 3
	v_readlane_b32 s16, v254, 4
	v_readlane_b32 s17, v254, 5
	v_readlane_b32 s18, v254, 6
	v_readlane_b32 s19, v254, 7
	v_mul_f32_e32 v16, v16, v123
.LBB0_1624:
	s_and_b64 vcc, exec, s[40:41]
	ds_write_b32 v4, v16 offset:47288
	s_cbranch_vccnz .LBB0_1626
	s_ashr_i32 s31, s30, 31
	v_readlane_b32 s4, v253, 56
	v_lshl_add_u64 v[6:7], v[2:3], 0, s[30:31]
	v_readlane_b32 s6, v253, 58
	v_readlane_b32 s7, v253, 59
	v_readlane_b32 s5, v253, 57
	v_readlane_b32 s8, v253, 60
	v_lshl_add_u64 v[6:7], v[6:7], 2, s[6:7]
	v_readlane_b32 s9, v253, 61
	v_readlane_b32 s10, v253, 62
	v_readlane_b32 s11, v253, 63
	v_readlane_b32 s12, v254, 0
	v_readlane_b32 s13, v254, 1
	v_readlane_b32 s14, v254, 2
	v_readlane_b32 s15, v254, 3
	v_readlane_b32 s16, v254, 4
	v_readlane_b32 s17, v254, 5
	v_readlane_b32 s18, v254, 6
	v_readlane_b32 s19, v254, 7
	v_mul_f32_e32 v15, v15, v124
.LBB0_1626:
	s_and_b64 vcc, exec, s[40:41]
	ds_write_b32 v4, v15 offset:49344
	s_cbranch_vccnz .LBB0_1628
	s_ashr_i32 s31, s30, 31
	v_readlane_b32 s4, v253, 56
	v_lshl_add_u64 v[6:7], v[2:3], 0, s[30:31]
	v_readlane_b32 s6, v253, 58
	v_readlane_b32 s7, v253, 59
	v_readlane_b32 s5, v253, 57
	v_readlane_b32 s8, v253, 60
	v_lshl_add_u64 v[6:7], v[6:7], 2, s[6:7]
	v_readlane_b32 s9, v253, 61
	v_readlane_b32 s10, v253, 62
	v_readlane_b32 s11, v253, 63
	v_readlane_b32 s12, v254, 0
	v_readlane_b32 s13, v254, 1
	v_readlane_b32 s14, v254, 2
	v_readlane_b32 s15, v254, 3
	v_readlane_b32 s16, v254, 4
	v_readlane_b32 s17, v254, 5
	v_readlane_b32 s18, v254, 6
	v_readlane_b32 s19, v254, 7
	v_mul_f32_e32 v14, v14, v125
.LBB0_1628:
	s_and_b64 vcc, exec, s[40:41]
	ds_write_b32 v4, v14 offset:51400
	s_cbranch_vccnz .LBB0_1630
	s_ashr_i32 s31, s30, 31
	v_readlane_b32 s4, v253, 56
	v_lshl_add_u64 v[6:7], v[2:3], 0, s[30:31]
	v_readlane_b32 s6, v253, 58
	v_readlane_b32 s7, v253, 59
	v_readlane_b32 s5, v253, 57
	v_readlane_b32 s8, v253, 60
	v_lshl_add_u64 v[6:7], v[6:7], 2, s[6:7]
	v_readlane_b32 s9, v253, 61
	v_readlane_b32 s10, v253, 62
	v_readlane_b32 s11, v253, 63
	v_readlane_b32 s12, v254, 0
	v_readlane_b32 s13, v254, 1
	v_readlane_b32 s14, v254, 2
	v_readlane_b32 s15, v254, 3
	v_readlane_b32 s16, v254, 4
	v_readlane_b32 s17, v254, 5
	v_readlane_b32 s18, v254, 6
	v_readlane_b32 s19, v254, 7
	v_mul_f32_e32 v13, v13, v126
; DI void convert_tile(const CvtJob& jb, int ti, char* lds) {
;     ...
; #pragma unroll
;   for (int i = 0; i < 32; ++i) v[i] = (n < N) ? jb.src[(size_t)(k0 + kr + 2 * i) * N + n] : 0.f;
; #pragma unroll
;   for (int i = 0; i < 32; ++i) { const int k = kr + 2 * i; tile[k * 257 + nn] = jb.kscale ? v[i] * jb.kscale[k0 + k] : v[i]; }
.LBB0_1630:
	s_and_b64 vcc, exec, s[40:41]
	ds_write_b32 v4, v13 offset:53456
	s_cbranch_vccnz .LBB0_1632
	s_ashr_i32 s31, s30, 31
	v_readlane_b32 s4, v253, 56
	v_lshl_add_u64 v[6:7], v[2:3], 0, s[30:31]
	v_readlane_b32 s6, v253, 58
	v_readlane_b32 s7, v253, 59
	v_readlane_b32 s5, v253, 57
	v_readlane_b32 s8, v253, 60
	v_lshl_add_u64 v[6:7], v[6:7], 2, s[6:7]
	v_readlane_b32 s9, v253, 61
	v_readlane_b32 s10, v253, 62
	v_readlane_b32 s11, v253, 63
	v_readlane_b32 s12, v254, 0
	v_readlane_b32 s13, v254, 1
	v_readlane_b32 s14, v254, 2
	v_readlane_b32 s15, v254, 3
	v_readlane_b32 s16, v254, 4
	v_readlane_b32 s17, v254, 5
	v_readlane_b32 s18, v254, 6
	v_readlane_b32 s19, v254, 7
	v_mul_f32_e32 v12, v12, v127
.LBB0_1632:
	s_and_b64 vcc, exec, s[40:41]
	ds_write_b32 v4, v12 offset:55512
	s_cbranch_vccnz .LBB0_1634
	s_ashr_i32 s31, s30, 31
	v_readlane_b32 s4, v253, 56
	v_lshl_add_u64 v[6:7], v[2:3], 0, s[30:31]
	v_readlane_b32 s6, v253, 58
	v_readlane_b32 s7, v253, 59
	v_readlane_b32 s5, v253, 57
	v_readlane_b32 s8, v253, 60
	v_lshl_add_u64 v[6:7], v[6:7], 2, s[6:7]
	v_readlane_b32 s9, v253, 61
	v_readlane_b32 s10, v253, 62
	v_readlane_b32 s11, v253, 63
	v_readlane_b32 s12, v254, 0
	v_readlane_b32 s13, v254, 1
	v_readlane_b32 s14, v254, 2
	v_readlane_b32 s15, v254, 3
	v_readlane_b32 s16, v254, 4
	v_readlane_b32 s17, v254, 5
	v_readlane_b32 s18, v254, 6
	v_readlane_b32 s19, v254, 7
	v_mul_f32_e32 v11, v11, v128
.LBB0_1634:
	s_and_b64 vcc, exec, s[40:41]
	ds_write_b32 v4, v11 offset:57568
	s_cbranch_vccnz .LBB0_1636
	s_ashr_i32 s31, s30, 31
	v_readlane_b32 s4, v253, 56
	v_lshl_add_u64 v[6:7], v[2:3], 0, s[30:31]
	v_readlane_b32 s6, v253, 58
	v_readlane_b32 s7, v253, 59
	v_readlane_b32 s5, v253, 57
	v_readlane_b32 s8, v253, 60
	v_lshl_add_u64 v[6:7], v[6:7], 2, s[6:7]
	v_readlane_b32 s9, v253, 61
	v_readlane_b32 s10, v253, 62
	v_readlane_b32 s11, v253, 63
	v_readlane_b32 s12, v254, 0
	v_readlane_b32 s13, v254, 1
	v_readlane_b32 s14, v254, 2
	v_readlane_b32 s15, v254, 3
	v_readlane_b32 s16, v254, 4
	v_readlane_b32 s17, v254, 5
	v_readlane_b32 s18, v254, 6
	v_readlane_b32 s19, v254, 7
	v_mul_f32_e32 v10, v10, v129
.LBB0_1636:
	s_and_b64 vcc, exec, s[40:41]
	ds_write_b32 v4, v10 offset:59624
	s_cbranch_vccnz .LBB0_1638
	s_ashr_i32 s31, s30, 31
	v_readlane_b32 s4, v253, 56
	v_lshl_add_u64 v[6:7], v[2:3], 0, s[30:31]
	v_readlane_b32 s6, v253, 58
	v_readlane_b32 s7, v253, 59
	v_readlane_b32 s5, v253, 57
	v_readlane_b32 s8, v253, 60
	v_lshl_add_u64 v[6:7], v[6:7], 2, s[6:7]
	v_readlane_b32 s9, v253, 61
	v_readlane_b32 s10, v253, 62
	v_readlane_b32 s11, v253, 63
	v_readlane_b32 s12, v254, 0
	v_readlane_b32 s13, v254, 1
	v_readlane_b32 s14, v254, 2
	v_readlane_b32 s15, v254, 3
	v_readlane_b32 s16, v254, 4
	v_readlane_b32 s17, v254, 5
	v_readlane_b32 s18, v254, 6
	v_readlane_b32 s19, v254, 7
	v_mul_f32_e32 v9, v9, v130
.LBB0_1638:
	v_readlane_b32 s4, v252, 33
	v_readlane_b32 s5, v252, 34
	s_and_b64 vcc, exec, s[4:5]
	ds_write_b32 v4, v9 offset:61680
	s_cbranch_vccz .LBB0_1729
	s_ashr_i32 s31, s30, 31
	v_readlane_b32 s4, v253, 56
	v_lshl_add_u64 v[2:3], v[2:3], 0, s[30:31]
	v_readlane_b32 s6, v253, 58
	v_readlane_b32 s7, v253, 59
	v_readlane_b32 s5, v253, 57
	v_readlane_b32 s8, v253, 60
	v_lshl_add_u64 v[2:3], v[2:3], 2, s[6:7]
	v_readlane_b32 s9, v253, 61
	v_readlane_b32 s10, v253, 62
	v_readlane_b32 s11, v253, 63
	v_readlane_b32 s12, v254, 0
	v_readlane_b32 s13, v254, 1
	v_readlane_b32 s14, v254, 2
	v_readlane_b32 s15, v254, 3
	v_readlane_b32 s16, v254, 4
	v_readlane_b32 s17, v254, 5
	v_readlane_b32 s18, v254, 6
	v_readlane_b32 s19, v254, 7
	v_mul_f32_e32 v2, v0, v131
	s_cbranch_execnz .LBB0_1641
